# scan: per-step scalars applied by DPP row_newbcast from their chunk vectors onto the MFMA result (32 v_readlane per chunk removed), chunk-end D15 read hoisted
# speedup vs baseline: 1.1043x; 1.0024x over previous
.LBB0_581:
	s_waitcnt vmcnt(63) expcnt(7) lgkmcnt(15)
	s_barrier
	s_and_saveexec_b64 s[12:13], s[0:1]
	s_xor_b64 s[12:13], exec, s[12:13]
	s_cbranch_execz .LBB0_584
	s_mov_b32 s16, 0
	v_mov_b32_e32 v2, 0
	s_mov_b32 s52, 0
	s_mov_b32 s17, 0
	v_mov_b32_e32 v3, 0
	v_mov_b32_e32 v4, 0
	v_mov_b32_e32 v5, 0
	v_mov_b32_e32 v6, 0
	v_mov_b32_e32 v7, 0
	v_mov_b32_e32 v8, 0
	v_mov_b32_e32 v9, 0
	v_mov_b32_e32 v10, 0
	v_mov_b32_e32 v11, 0
	v_mov_b32_e32 v12, 0
	v_mov_b32_e32 v13, 0
	v_mov_b32_e32 v14, 0
	v_mov_b32_e32 v15, 0
	v_mov_b32_e32 v16, 0
	v_mov_b32_e32 v17, 0
	v_mov_b32_e32 v18, 0
	v_mov_b32_e32 v22, 0
	v_mov_b32_e32 v19, 0
	v_mov_b32_e32 v228, 1.0
	v_mov_b32_e32 v229, 0
	v_mov_b32_e32 v230, 0
	v_mov_b32_e32 v224, 0
	v_mov_b32_e32 v232, 0
	s_barrier
.LBB0_583:
	s_and_b32 s48, s16, 1
	v_lshl_add_u32 v21, s48, 9, v135
	ds_read_b128 v[24:27], v21
	ds_read_b128 v[28:31], v21 offset:16
	v_fmac_f32_dpp v224, v229, v232 row_newbcast:15 row_mask:0xf bank_mask:0xf bound_ctrl:1
	s_mul_i32 s52, s48, 0x6000
	v_fmac_f32_dpp v224, v230, v19 row_newbcast:15 row_mask:0xf bank_mask:0xf bound_ctrl:1
	s_add_i32 s17, s52, 0
	v_add3_u32 v19, s17, v157, v72
	v_lshl_add_u32 v21, v73, 2, s17
	ds_read2st64_b32 v[32:33], v19 offset0:80 offset1:81
	ds_read2st64_b32 v[34:35], v21 offset0:16 offset1:17
	ds_read2st64_b32 v[36:37], v21 offset0:32 offset1:33
	ds_read2st64_b32 v[38:39], v21 offset0:48 offset1:49
	ds_read2st64_b32 v[40:41], v21 offset0:64 offset1:65
	s_waitcnt lgkmcnt(6)
	v_mov_b32_e32 v42, v24
	s_waitcnt lgkmcnt(5)
	v_mov_b32_e32 v43, v28
	v_mov_b32_e32 v44, v26
	v_mov_b32_e32 v45, v30
	v_mov_b32_e32 v28, v25
	v_mov_b32_e32 v30, v27
	v_pk_add_f32 v[24:25], v[42:43], v[44:45]
	v_pk_add_f32 v[26:27], v[28:29], v[30:31]
	s_waitcnt lgkmcnt(3)
	v_mul_f32_dpp v42, v34, v17 row_newbcast:0 row_mask:0xf bank_mask:0xf bound_ctrl:1
	v_add_f32_e32 v23, v24, v25
	v_add_f32_e32 v24, v26, v27
	v_mul_f32_dpp v25, v34, v16 row_newbcast:1 row_mask:0xf bank_mask:0xf bound_ctrl:1
	v_fmac_f32_dpp v42, v34, v15 row_newbcast:2 row_mask:0xf bank_mask:0xf bound_ctrl:1
	v_fmac_f32_dpp v25, v34, v14 row_newbcast:3 row_mask:0xf bank_mask:0xf bound_ctrl:1
	v_fmac_f32_dpp v42, v34, v13 row_newbcast:4 row_mask:0xf bank_mask:0xf bound_ctrl:1
	v_xor_b32_e32 v229, 0x80000000, v23
	v_fmac_f32_dpp v25, v34, v12 row_newbcast:5 row_mask:0xf bank_mask:0xf bound_ctrl:1
	v_fmac_f32_dpp v42, v34, v11 row_newbcast:6 row_mask:0xf bank_mask:0xf bound_ctrl:1
	v_fmac_f32_dpp v25, v34, v10 row_newbcast:7 row_mask:0xf bank_mask:0xf bound_ctrl:1
	v_fmac_f32_dpp v42, v34, v9 row_newbcast:8 row_mask:0xf bank_mask:0xf bound_ctrl:1
	v_xor_b32_e32 v230, 0x80000000, v24
	v_fmac_f32_dpp v25, v34, v8 row_newbcast:9 row_mask:0xf bank_mask:0xf bound_ctrl:1
	v_fmac_f32_dpp v42, v34, v7 row_newbcast:10 row_mask:0xf bank_mask:0xf bound_ctrl:1
	v_fmac_f32_dpp v25, v34, v6 row_newbcast:11 row_mask:0xf bank_mask:0xf bound_ctrl:1
	v_fmac_f32_dpp v42, v34, v5 row_newbcast:12 row_mask:0xf bank_mask:0xf bound_ctrl:1
	v_fmac_f32_dpp v25, v34, v4 row_newbcast:13 row_mask:0xf bank_mask:0xf bound_ctrl:1
	v_fmac_f32_dpp v42, v34, v3 row_newbcast:14 row_mask:0xf bank_mask:0xf bound_ctrl:1
	v_fmac_f32_dpp v25, v34, v2 row_newbcast:15 row_mask:0xf bank_mask:0xf bound_ctrl:1
	s_waitcnt lgkmcnt(2)
	v_fmac_f32_dpp v17, v36, v224 row_newbcast:0 row_mask:0xf bank_mask:0xf bound_ctrl:1
	v_fmac_f32_dpp v16, v36, v224 row_newbcast:1 row_mask:0xf bank_mask:0xf bound_ctrl:1
	v_fmac_f32_dpp v15, v36, v224 row_newbcast:2 row_mask:0xf bank_mask:0xf bound_ctrl:1
	v_fmac_f32_dpp v14, v36, v224 row_newbcast:3 row_mask:0xf bank_mask:0xf bound_ctrl:1
	v_fmac_f32_dpp v13, v36, v224 row_newbcast:4 row_mask:0xf bank_mask:0xf bound_ctrl:1
	v_fmac_f32_dpp v12, v36, v224 row_newbcast:5 row_mask:0xf bank_mask:0xf bound_ctrl:1
	v_fmac_f32_dpp v11, v36, v224 row_newbcast:6 row_mask:0xf bank_mask:0xf bound_ctrl:1
	v_fmac_f32_dpp v10, v36, v224 row_newbcast:7 row_mask:0xf bank_mask:0xf bound_ctrl:1
	v_fmac_f32_dpp v9, v36, v224 row_newbcast:8 row_mask:0xf bank_mask:0xf bound_ctrl:1
	v_fmac_f32_dpp v8, v36, v224 row_newbcast:9 row_mask:0xf bank_mask:0xf bound_ctrl:1
	v_fmac_f32_dpp v7, v36, v224 row_newbcast:10 row_mask:0xf bank_mask:0xf bound_ctrl:1
	v_fmac_f32_dpp v6, v36, v224 row_newbcast:11 row_mask:0xf bank_mask:0xf bound_ctrl:1
	v_fmac_f32_dpp v5, v36, v224 row_newbcast:12 row_mask:0xf bank_mask:0xf bound_ctrl:1
	v_fmac_f32_dpp v4, v36, v224 row_newbcast:13 row_mask:0xf bank_mask:0xf bound_ctrl:1
	v_fmac_f32_dpp v3, v36, v224 row_newbcast:14 row_mask:0xf bank_mask:0xf bound_ctrl:1
	v_fmac_f32_dpp v2, v36, v224 row_newbcast:15 row_mask:0xf bank_mask:0xf bound_ctrl:1
	v_add_f32 v42, v42, v25
	v_lshl_add_u32 v22, s48, 15, v134
	s_nop 1
	v_mfma_f32_16x16x4_f32 v[232:235], v228, v42, 0
	s_waitcnt lgkmcnt(1)
	v_fmac_f32_dpp v17, v38, v32 row_newbcast:0 row_mask:0xf bank_mask:0xf bound_ctrl:1
	v_fmac_f32_dpp v16, v38, v32 row_newbcast:1 row_mask:0xf bank_mask:0xf bound_ctrl:1
	v_fmac_f32_dpp v15, v38, v32 row_newbcast:2 row_mask:0xf bank_mask:0xf bound_ctrl:1
	v_fmac_f32_dpp v14, v38, v32 row_newbcast:3 row_mask:0xf bank_mask:0xf bound_ctrl:1
	v_fmac_f32_dpp v13, v38, v32 row_newbcast:4 row_mask:0xf bank_mask:0xf bound_ctrl:1
	v_fmac_f32_dpp v12, v38, v32 row_newbcast:5 row_mask:0xf bank_mask:0xf bound_ctrl:1
	v_fmac_f32_dpp v11, v38, v32 row_newbcast:6 row_mask:0xf bank_mask:0xf bound_ctrl:1
	v_fmac_f32_dpp v10, v38, v32 row_newbcast:7 row_mask:0xf bank_mask:0xf bound_ctrl:1
	v_fmac_f32_dpp v9, v38, v32 row_newbcast:8 row_mask:0xf bank_mask:0xf bound_ctrl:1
	v_fmac_f32_dpp v8, v38, v32 row_newbcast:9 row_mask:0xf bank_mask:0xf bound_ctrl:1
	v_fmac_f32_dpp v7, v38, v32 row_newbcast:10 row_mask:0xf bank_mask:0xf bound_ctrl:1
	v_fmac_f32_dpp v6, v38, v32 row_newbcast:11 row_mask:0xf bank_mask:0xf bound_ctrl:1
	v_fmac_f32_dpp v5, v38, v32 row_newbcast:12 row_mask:0xf bank_mask:0xf bound_ctrl:1
	v_fmac_f32_dpp v4, v38, v32 row_newbcast:13 row_mask:0xf bank_mask:0xf bound_ctrl:1
	v_fmac_f32_dpp v3, v38, v32 row_newbcast:14 row_mask:0xf bank_mask:0xf bound_ctrl:1
	v_fmac_f32_dpp v2, v38, v32 row_newbcast:15 row_mask:0xf bank_mask:0xf bound_ctrl:1
	s_waitcnt lgkmcnt(0)
	v_mul_f32_dpp v24, v40, v17 row_newbcast:0 row_mask:0xf bank_mask:0xf bound_ctrl:1
	v_mul_f32_dpp v25, v40, v16 row_newbcast:1 row_mask:0xf bank_mask:0xf bound_ctrl:1
	v_fmac_f32_dpp v24, v40, v15 row_newbcast:2 row_mask:0xf bank_mask:0xf bound_ctrl:1
	v_fmac_f32_dpp v25, v40, v14 row_newbcast:3 row_mask:0xf bank_mask:0xf bound_ctrl:1
	v_fmac_f32_dpp v24, v40, v13 row_newbcast:4 row_mask:0xf bank_mask:0xf bound_ctrl:1
	v_fmac_f32_dpp v25, v40, v12 row_newbcast:5 row_mask:0xf bank_mask:0xf bound_ctrl:1
	v_fmac_f32_dpp v24, v40, v11 row_newbcast:6 row_mask:0xf bank_mask:0xf bound_ctrl:1
	v_fmac_f32_dpp v25, v40, v10 row_newbcast:7 row_mask:0xf bank_mask:0xf bound_ctrl:1
	v_add_u32_e32 v20, 0xc000, v22
	v_fmac_f32_dpp v24, v40, v9 row_newbcast:8 row_mask:0xf bank_mask:0xf bound_ctrl:1
	v_fmac_f32_dpp v25, v40, v8 row_newbcast:9 row_mask:0xf bank_mask:0xf bound_ctrl:1
	v_fmac_f32_dpp v24, v40, v7 row_newbcast:10 row_mask:0xf bank_mask:0xf bound_ctrl:1
	v_fmac_f32_dpp v25, v40, v6 row_newbcast:11 row_mask:0xf bank_mask:0xf bound_ctrl:1
	s_add_i32 s16, s16, 1
	v_fmac_f32_dpp v24, v40, v5 row_newbcast:12 row_mask:0xf bank_mask:0xf bound_ctrl:1
	v_fmac_f32_dpp v25, v40, v4 row_newbcast:13 row_mask:0xf bank_mask:0xf bound_ctrl:1
	v_fmac_f32_dpp v24, v40, v3 row_newbcast:14 row_mask:0xf bank_mask:0xf bound_ctrl:1
	v_fmac_f32_dpp v25, v40, v2 row_newbcast:15 row_mask:0xf bank_mask:0xf bound_ctrl:1
	ds_read_b32 v36, v19 offset:20992
	ds_read2st64_b32 v[26:27], v21 offset0:18 offset1:34
	ds_read2st64_b32 v[28:29], v21 offset0:50 offset1:66
	v_mul_f32_dpp v38, v35, v17 row_newbcast:0 row_mask:0xf bank_mask:0xf bound_ctrl:1
	v_mul_f32_dpp v31, v35, v16 row_newbcast:1 row_mask:0xf bank_mask:0xf bound_ctrl:1
	v_fmac_f32_dpp v38, v35, v15 row_newbcast:2 row_mask:0xf bank_mask:0xf bound_ctrl:1
	v_fmac_f32_dpp v31, v35, v14 row_newbcast:3 row_mask:0xf bank_mask:0xf bound_ctrl:1
	v_fmac_f32_dpp v232, v229, v224 row_newbcast:0 row_mask:0xf bank_mask:0xf bound_ctrl:1
	v_fmac_f32_dpp v38, v35, v13 row_newbcast:4 row_mask:0xf bank_mask:0xf bound_ctrl:1
	v_fmac_f32_dpp v31, v35, v12 row_newbcast:5 row_mask:0xf bank_mask:0xf bound_ctrl:1
	v_fmac_f32_dpp v38, v35, v11 row_newbcast:6 row_mask:0xf bank_mask:0xf bound_ctrl:1
	v_fmac_f32_dpp v31, v35, v10 row_newbcast:7 row_mask:0xf bank_mask:0xf bound_ctrl:1
	v_fmac_f32_dpp v232, v230, v32 row_newbcast:0 row_mask:0xf bank_mask:0xf bound_ctrl:1
	v_fmac_f32_dpp v38, v35, v9 row_newbcast:8 row_mask:0xf bank_mask:0xf bound_ctrl:1
	v_fmac_f32_dpp v31, v35, v8 row_newbcast:9 row_mask:0xf bank_mask:0xf bound_ctrl:1
	v_fmac_f32_dpp v38, v35, v7 row_newbcast:10 row_mask:0xf bank_mask:0xf bound_ctrl:1
	v_fmac_f32_dpp v31, v35, v6 row_newbcast:11 row_mask:0xf bank_mask:0xf bound_ctrl:1
	s_cmpk_lg_i32 s16, 0x210
	v_fmac_f32_dpp v38, v35, v5 row_newbcast:12 row_mask:0xf bank_mask:0xf bound_ctrl:1
	v_fmac_f32_dpp v31, v35, v4 row_newbcast:13 row_mask:0xf bank_mask:0xf bound_ctrl:1
	v_fmac_f32_dpp v38, v35, v3 row_newbcast:14 row_mask:0xf bank_mask:0xf bound_ctrl:1
	v_fmac_f32_dpp v31, v35, v2 row_newbcast:15 row_mask:0xf bank_mask:0xf bound_ctrl:1
	v_fmac_f32_dpp v17, v37, v232 row_newbcast:0 row_mask:0xf bank_mask:0xf bound_ctrl:1
	v_fmac_f32_dpp v16, v37, v232 row_newbcast:1 row_mask:0xf bank_mask:0xf bound_ctrl:1
	v_fmac_f32_dpp v15, v37, v232 row_newbcast:2 row_mask:0xf bank_mask:0xf bound_ctrl:1
	v_fmac_f32_dpp v14, v37, v232 row_newbcast:3 row_mask:0xf bank_mask:0xf bound_ctrl:1
	v_fmac_f32_dpp v13, v37, v232 row_newbcast:4 row_mask:0xf bank_mask:0xf bound_ctrl:1
	v_fmac_f32_dpp v12, v37, v232 row_newbcast:5 row_mask:0xf bank_mask:0xf bound_ctrl:1
	v_fmac_f32_dpp v11, v37, v232 row_newbcast:6 row_mask:0xf bank_mask:0xf bound_ctrl:1
	v_fmac_f32_dpp v10, v37, v232 row_newbcast:7 row_mask:0xf bank_mask:0xf bound_ctrl:1
	v_fmac_f32_dpp v9, v37, v232 row_newbcast:8 row_mask:0xf bank_mask:0xf bound_ctrl:1
	v_fmac_f32_dpp v8, v37, v232 row_newbcast:9 row_mask:0xf bank_mask:0xf bound_ctrl:1
	v_fmac_f32_dpp v7, v37, v232 row_newbcast:10 row_mask:0xf bank_mask:0xf bound_ctrl:1
	v_fmac_f32_dpp v6, v37, v232 row_newbcast:11 row_mask:0xf bank_mask:0xf bound_ctrl:1
	v_fmac_f32_dpp v5, v37, v232 row_newbcast:12 row_mask:0xf bank_mask:0xf bound_ctrl:1
	v_fmac_f32_dpp v4, v37, v232 row_newbcast:13 row_mask:0xf bank_mask:0xf bound_ctrl:1
	v_fmac_f32_dpp v3, v37, v232 row_newbcast:14 row_mask:0xf bank_mask:0xf bound_ctrl:1
	v_fmac_f32_dpp v2, v37, v232 row_newbcast:15 row_mask:0xf bank_mask:0xf bound_ctrl:1
	s_nop 0
	v_add_f32 v38, v38, v31
	s_nop 0
	s_nop 0
	v_mfma_f32_16x16x4_f32 v[224:227], v228, v38, 0
	ds_write_b64 v22, v[24:25] offset:49152
	v_fmac_f32_dpp v17, v39, v33 row_newbcast:0 row_mask:0xf bank_mask:0xf bound_ctrl:1
	v_fmac_f32_dpp v16, v39, v33 row_newbcast:1 row_mask:0xf bank_mask:0xf bound_ctrl:1
	v_fmac_f32_dpp v15, v39, v33 row_newbcast:2 row_mask:0xf bank_mask:0xf bound_ctrl:1
	v_fmac_f32_dpp v14, v39, v33 row_newbcast:3 row_mask:0xf bank_mask:0xf bound_ctrl:1
	v_fmac_f32_dpp v13, v39, v33 row_newbcast:4 row_mask:0xf bank_mask:0xf bound_ctrl:1
	v_fmac_f32_dpp v12, v39, v33 row_newbcast:5 row_mask:0xf bank_mask:0xf bound_ctrl:1
	v_fmac_f32_dpp v11, v39, v33 row_newbcast:6 row_mask:0xf bank_mask:0xf bound_ctrl:1
	v_fmac_f32_dpp v10, v39, v33 row_newbcast:7 row_mask:0xf bank_mask:0xf bound_ctrl:1
	v_fmac_f32_dpp v9, v39, v33 row_newbcast:8 row_mask:0xf bank_mask:0xf bound_ctrl:1
	v_fmac_f32_dpp v8, v39, v33 row_newbcast:9 row_mask:0xf bank_mask:0xf bound_ctrl:1
	v_fmac_f32_dpp v7, v39, v33 row_newbcast:10 row_mask:0xf bank_mask:0xf bound_ctrl:1
	v_fmac_f32_dpp v6, v39, v33 row_newbcast:11 row_mask:0xf bank_mask:0xf bound_ctrl:1
	v_fmac_f32_dpp v5, v39, v33 row_newbcast:12 row_mask:0xf bank_mask:0xf bound_ctrl:1
	v_fmac_f32_dpp v4, v39, v33 row_newbcast:13 row_mask:0xf bank_mask:0xf bound_ctrl:1
	v_fmac_f32_dpp v3, v39, v33 row_newbcast:14 row_mask:0xf bank_mask:0xf bound_ctrl:1
	v_fmac_f32_dpp v2, v39, v33 row_newbcast:15 row_mask:0xf bank_mask:0xf bound_ctrl:1
	v_mul_f32_dpp v24, v41, v17 row_newbcast:0 row_mask:0xf bank_mask:0xf bound_ctrl:1
	v_mul_f32_dpp v25, v41, v16 row_newbcast:1 row_mask:0xf bank_mask:0xf bound_ctrl:1
	v_fmac_f32_dpp v24, v41, v15 row_newbcast:2 row_mask:0xf bank_mask:0xf bound_ctrl:1
	v_fmac_f32_dpp v25, v41, v14 row_newbcast:3 row_mask:0xf bank_mask:0xf bound_ctrl:1
	v_fmac_f32_dpp v24, v41, v13 row_newbcast:4 row_mask:0xf bank_mask:0xf bound_ctrl:1
	v_fmac_f32_dpp v25, v41, v12 row_newbcast:5 row_mask:0xf bank_mask:0xf bound_ctrl:1
	v_fmac_f32_dpp v24, v41, v11 row_newbcast:6 row_mask:0xf bank_mask:0xf bound_ctrl:1
	v_fmac_f32_dpp v25, v41, v10 row_newbcast:7 row_mask:0xf bank_mask:0xf bound_ctrl:1
	s_nop 0
	v_fmac_f32_dpp v24, v41, v9 row_newbcast:8 row_mask:0xf bank_mask:0xf bound_ctrl:1
	v_fmac_f32_dpp v25, v41, v8 row_newbcast:9 row_mask:0xf bank_mask:0xf bound_ctrl:1
	v_fmac_f32_dpp v24, v41, v7 row_newbcast:10 row_mask:0xf bank_mask:0xf bound_ctrl:1
	v_fmac_f32_dpp v25, v41, v6 row_newbcast:11 row_mask:0xf bank_mask:0xf bound_ctrl:1
	s_nop 0
	v_fmac_f32_dpp v24, v41, v5 row_newbcast:12 row_mask:0xf bank_mask:0xf bound_ctrl:1
	v_fmac_f32_dpp v25, v41, v4 row_newbcast:13 row_mask:0xf bank_mask:0xf bound_ctrl:1
	v_fmac_f32_dpp v24, v41, v3 row_newbcast:14 row_mask:0xf bank_mask:0xf bound_ctrl:1
	v_fmac_f32_dpp v25, v41, v2 row_newbcast:15 row_mask:0xf bank_mask:0xf bound_ctrl:1
	s_waitcnt lgkmcnt(0)
	ds_read_b32 v37, v19 offset:21248
	ds_read2st64_b32 v[30:31], v21 offset0:19 offset1:35
	ds_read2st64_b32 v[34:35], v21 offset0:51 offset1:67
	v_mul_f32_dpp v39, v26, v17 row_newbcast:0 row_mask:0xf bank_mask:0xf bound_ctrl:1
	v_mul_f32_dpp v32, v26, v16 row_newbcast:1 row_mask:0xf bank_mask:0xf bound_ctrl:1
	v_fmac_f32_dpp v39, v26, v15 row_newbcast:2 row_mask:0xf bank_mask:0xf bound_ctrl:1
	v_fmac_f32_dpp v32, v26, v14 row_newbcast:3 row_mask:0xf bank_mask:0xf bound_ctrl:1
	v_fmac_f32_dpp v224, v229, v232 row_newbcast:1 row_mask:0xf bank_mask:0xf bound_ctrl:1
	v_fmac_f32_dpp v39, v26, v13 row_newbcast:4 row_mask:0xf bank_mask:0xf bound_ctrl:1
	v_fmac_f32_dpp v32, v26, v12 row_newbcast:5 row_mask:0xf bank_mask:0xf bound_ctrl:1
	v_fmac_f32_dpp v39, v26, v11 row_newbcast:6 row_mask:0xf bank_mask:0xf bound_ctrl:1
	v_fmac_f32_dpp v32, v26, v10 row_newbcast:7 row_mask:0xf bank_mask:0xf bound_ctrl:1
	v_fmac_f32_dpp v224, v230, v33 row_newbcast:1 row_mask:0xf bank_mask:0xf bound_ctrl:1
	v_fmac_f32_dpp v39, v26, v9 row_newbcast:8 row_mask:0xf bank_mask:0xf bound_ctrl:1
	v_fmac_f32_dpp v32, v26, v8 row_newbcast:9 row_mask:0xf bank_mask:0xf bound_ctrl:1
	v_fmac_f32_dpp v39, v26, v7 row_newbcast:10 row_mask:0xf bank_mask:0xf bound_ctrl:1
	v_fmac_f32_dpp v32, v26, v6 row_newbcast:11 row_mask:0xf bank_mask:0xf bound_ctrl:1
	s_nop 0
	v_fmac_f32_dpp v39, v26, v5 row_newbcast:12 row_mask:0xf bank_mask:0xf bound_ctrl:1
	v_fmac_f32_dpp v32, v26, v4 row_newbcast:13 row_mask:0xf bank_mask:0xf bound_ctrl:1
	v_fmac_f32_dpp v39, v26, v3 row_newbcast:14 row_mask:0xf bank_mask:0xf bound_ctrl:1
	v_fmac_f32_dpp v32, v26, v2 row_newbcast:15 row_mask:0xf bank_mask:0xf bound_ctrl:1
	v_fmac_f32_dpp v17, v27, v224 row_newbcast:0 row_mask:0xf bank_mask:0xf bound_ctrl:1
	v_fmac_f32_dpp v16, v27, v224 row_newbcast:1 row_mask:0xf bank_mask:0xf bound_ctrl:1
	v_fmac_f32_dpp v15, v27, v224 row_newbcast:2 row_mask:0xf bank_mask:0xf bound_ctrl:1
	v_fmac_f32_dpp v14, v27, v224 row_newbcast:3 row_mask:0xf bank_mask:0xf bound_ctrl:1
	v_fmac_f32_dpp v13, v27, v224 row_newbcast:4 row_mask:0xf bank_mask:0xf bound_ctrl:1
	v_fmac_f32_dpp v12, v27, v224 row_newbcast:5 row_mask:0xf bank_mask:0xf bound_ctrl:1
	v_fmac_f32_dpp v11, v27, v224 row_newbcast:6 row_mask:0xf bank_mask:0xf bound_ctrl:1
	v_fmac_f32_dpp v10, v27, v224 row_newbcast:7 row_mask:0xf bank_mask:0xf bound_ctrl:1
	v_fmac_f32_dpp v9, v27, v224 row_newbcast:8 row_mask:0xf bank_mask:0xf bound_ctrl:1
	v_fmac_f32_dpp v8, v27, v224 row_newbcast:9 row_mask:0xf bank_mask:0xf bound_ctrl:1
	v_fmac_f32_dpp v7, v27, v224 row_newbcast:10 row_mask:0xf bank_mask:0xf bound_ctrl:1
	v_fmac_f32_dpp v6, v27, v224 row_newbcast:11 row_mask:0xf bank_mask:0xf bound_ctrl:1
	v_fmac_f32_dpp v5, v27, v224 row_newbcast:12 row_mask:0xf bank_mask:0xf bound_ctrl:1
	v_fmac_f32_dpp v4, v27, v224 row_newbcast:13 row_mask:0xf bank_mask:0xf bound_ctrl:1
	v_fmac_f32_dpp v3, v27, v224 row_newbcast:14 row_mask:0xf bank_mask:0xf bound_ctrl:1
	v_fmac_f32_dpp v2, v27, v224 row_newbcast:15 row_mask:0xf bank_mask:0xf bound_ctrl:1
	s_nop 0
	v_add_f32 v39, v39, v32
	s_nop 0
	s_nop 0
	v_mfma_f32_16x16x4_f32 v[232:235], v228, v39, 0
	ds_write_b64 v22, v[24:25] offset:51200
	v_fmac_f32_dpp v17, v28, v36 row_newbcast:0 row_mask:0xf bank_mask:0xf bound_ctrl:1
	v_fmac_f32_dpp v16, v28, v36 row_newbcast:1 row_mask:0xf bank_mask:0xf bound_ctrl:1
	v_fmac_f32_dpp v15, v28, v36 row_newbcast:2 row_mask:0xf bank_mask:0xf bound_ctrl:1
	v_fmac_f32_dpp v14, v28, v36 row_newbcast:3 row_mask:0xf bank_mask:0xf bound_ctrl:1
	v_fmac_f32_dpp v13, v28, v36 row_newbcast:4 row_mask:0xf bank_mask:0xf bound_ctrl:1
	v_fmac_f32_dpp v12, v28, v36 row_newbcast:5 row_mask:0xf bank_mask:0xf bound_ctrl:1
	v_fmac_f32_dpp v11, v28, v36 row_newbcast:6 row_mask:0xf bank_mask:0xf bound_ctrl:1
	v_fmac_f32_dpp v10, v28, v36 row_newbcast:7 row_mask:0xf bank_mask:0xf bound_ctrl:1
	v_fmac_f32_dpp v9, v28, v36 row_newbcast:8 row_mask:0xf bank_mask:0xf bound_ctrl:1
	v_fmac_f32_dpp v8, v28, v36 row_newbcast:9 row_mask:0xf bank_mask:0xf bound_ctrl:1
	v_fmac_f32_dpp v7, v28, v36 row_newbcast:10 row_mask:0xf bank_mask:0xf bound_ctrl:1
	v_fmac_f32_dpp v6, v28, v36 row_newbcast:11 row_mask:0xf bank_mask:0xf bound_ctrl:1
	v_fmac_f32_dpp v5, v28, v36 row_newbcast:12 row_mask:0xf bank_mask:0xf bound_ctrl:1
	v_fmac_f32_dpp v4, v28, v36 row_newbcast:13 row_mask:0xf bank_mask:0xf bound_ctrl:1
	v_fmac_f32_dpp v3, v28, v36 row_newbcast:14 row_mask:0xf bank_mask:0xf bound_ctrl:1
	v_fmac_f32_dpp v2, v28, v36 row_newbcast:15 row_mask:0xf bank_mask:0xf bound_ctrl:1
	v_mul_f32_dpp v24, v29, v17 row_newbcast:0 row_mask:0xf bank_mask:0xf bound_ctrl:1
	v_mul_f32_dpp v25, v29, v16 row_newbcast:1 row_mask:0xf bank_mask:0xf bound_ctrl:1
	v_fmac_f32_dpp v24, v29, v15 row_newbcast:2 row_mask:0xf bank_mask:0xf bound_ctrl:1
	v_fmac_f32_dpp v25, v29, v14 row_newbcast:3 row_mask:0xf bank_mask:0xf bound_ctrl:1
	v_fmac_f32_dpp v24, v29, v13 row_newbcast:4 row_mask:0xf bank_mask:0xf bound_ctrl:1
	v_fmac_f32_dpp v25, v29, v12 row_newbcast:5 row_mask:0xf bank_mask:0xf bound_ctrl:1
	v_fmac_f32_dpp v24, v29, v11 row_newbcast:6 row_mask:0xf bank_mask:0xf bound_ctrl:1
	v_fmac_f32_dpp v25, v29, v10 row_newbcast:7 row_mask:0xf bank_mask:0xf bound_ctrl:1
	s_nop 0
	v_fmac_f32_dpp v24, v29, v9 row_newbcast:8 row_mask:0xf bank_mask:0xf bound_ctrl:1
	v_fmac_f32_dpp v25, v29, v8 row_newbcast:9 row_mask:0xf bank_mask:0xf bound_ctrl:1
	v_fmac_f32_dpp v24, v29, v7 row_newbcast:10 row_mask:0xf bank_mask:0xf bound_ctrl:1
	v_fmac_f32_dpp v25, v29, v6 row_newbcast:11 row_mask:0xf bank_mask:0xf bound_ctrl:1
	s_nop 0
	v_fmac_f32_dpp v24, v29, v5 row_newbcast:12 row_mask:0xf bank_mask:0xf bound_ctrl:1
	v_fmac_f32_dpp v25, v29, v4 row_newbcast:13 row_mask:0xf bank_mask:0xf bound_ctrl:1
	v_fmac_f32_dpp v24, v29, v3 row_newbcast:14 row_mask:0xf bank_mask:0xf bound_ctrl:1
	v_fmac_f32_dpp v25, v29, v2 row_newbcast:15 row_mask:0xf bank_mask:0xf bound_ctrl:1
	s_waitcnt lgkmcnt(0)
	ds_read_b32 v40, v19 offset:21504
	ds_read2st64_b32 v[26:27], v21 offset0:20 offset1:36
	ds_read2st64_b32 v[28:29], v21 offset0:52 offset1:68
	v_mul_f32_dpp v41, v30, v17 row_newbcast:0 row_mask:0xf bank_mask:0xf bound_ctrl:1
	v_mul_f32_dpp v32, v30, v16 row_newbcast:1 row_mask:0xf bank_mask:0xf bound_ctrl:1
	v_fmac_f32_dpp v41, v30, v15 row_newbcast:2 row_mask:0xf bank_mask:0xf bound_ctrl:1
	v_fmac_f32_dpp v32, v30, v14 row_newbcast:3 row_mask:0xf bank_mask:0xf bound_ctrl:1
	v_fmac_f32_dpp v232, v229, v224 row_newbcast:2 row_mask:0xf bank_mask:0xf bound_ctrl:1
	v_fmac_f32_dpp v41, v30, v13 row_newbcast:4 row_mask:0xf bank_mask:0xf bound_ctrl:1
	v_fmac_f32_dpp v32, v30, v12 row_newbcast:5 row_mask:0xf bank_mask:0xf bound_ctrl:1
	v_fmac_f32_dpp v41, v30, v11 row_newbcast:6 row_mask:0xf bank_mask:0xf bound_ctrl:1
	v_fmac_f32_dpp v32, v30, v10 row_newbcast:7 row_mask:0xf bank_mask:0xf bound_ctrl:1
	v_fmac_f32_dpp v232, v230, v36 row_newbcast:2 row_mask:0xf bank_mask:0xf bound_ctrl:1
	v_fmac_f32_dpp v41, v30, v9 row_newbcast:8 row_mask:0xf bank_mask:0xf bound_ctrl:1
	v_fmac_f32_dpp v32, v30, v8 row_newbcast:9 row_mask:0xf bank_mask:0xf bound_ctrl:1
	v_fmac_f32_dpp v41, v30, v7 row_newbcast:10 row_mask:0xf bank_mask:0xf bound_ctrl:1
	v_fmac_f32_dpp v32, v30, v6 row_newbcast:11 row_mask:0xf bank_mask:0xf bound_ctrl:1
	s_nop 0
	v_fmac_f32_dpp v41, v30, v5 row_newbcast:12 row_mask:0xf bank_mask:0xf bound_ctrl:1
	v_fmac_f32_dpp v32, v30, v4 row_newbcast:13 row_mask:0xf bank_mask:0xf bound_ctrl:1
	v_fmac_f32_dpp v41, v30, v3 row_newbcast:14 row_mask:0xf bank_mask:0xf bound_ctrl:1
	v_fmac_f32_dpp v32, v30, v2 row_newbcast:15 row_mask:0xf bank_mask:0xf bound_ctrl:1
	v_fmac_f32_dpp v17, v31, v232 row_newbcast:0 row_mask:0xf bank_mask:0xf bound_ctrl:1
	v_fmac_f32_dpp v16, v31, v232 row_newbcast:1 row_mask:0xf bank_mask:0xf bound_ctrl:1
	v_fmac_f32_dpp v15, v31, v232 row_newbcast:2 row_mask:0xf bank_mask:0xf bound_ctrl:1
	v_fmac_f32_dpp v14, v31, v232 row_newbcast:3 row_mask:0xf bank_mask:0xf bound_ctrl:1
	v_fmac_f32_dpp v13, v31, v232 row_newbcast:4 row_mask:0xf bank_mask:0xf bound_ctrl:1
	v_fmac_f32_dpp v12, v31, v232 row_newbcast:5 row_mask:0xf bank_mask:0xf bound_ctrl:1
	v_fmac_f32_dpp v11, v31, v232 row_newbcast:6 row_mask:0xf bank_mask:0xf bound_ctrl:1
	v_fmac_f32_dpp v10, v31, v232 row_newbcast:7 row_mask:0xf bank_mask:0xf bound_ctrl:1
	v_fmac_f32_dpp v9, v31, v232 row_newbcast:8 row_mask:0xf bank_mask:0xf bound_ctrl:1
	v_fmac_f32_dpp v8, v31, v232 row_newbcast:9 row_mask:0xf bank_mask:0xf bound_ctrl:1
	v_fmac_f32_dpp v7, v31, v232 row_newbcast:10 row_mask:0xf bank_mask:0xf bound_ctrl:1
	v_fmac_f32_dpp v6, v31, v232 row_newbcast:11 row_mask:0xf bank_mask:0xf bound_ctrl:1
	v_fmac_f32_dpp v5, v31, v232 row_newbcast:12 row_mask:0xf bank_mask:0xf bound_ctrl:1
	v_fmac_f32_dpp v4, v31, v232 row_newbcast:13 row_mask:0xf bank_mask:0xf bound_ctrl:1
	v_fmac_f32_dpp v3, v31, v232 row_newbcast:14 row_mask:0xf bank_mask:0xf bound_ctrl:1
	v_fmac_f32_dpp v2, v31, v232 row_newbcast:15 row_mask:0xf bank_mask:0xf bound_ctrl:1
	s_nop 0
	v_add_f32 v41, v41, v32
	s_nop 0
	s_nop 0
	v_mfma_f32_16x16x4_f32 v[224:227], v228, v41, 0
	ds_write_b64 v22, v[24:25] offset:53248
	v_fmac_f32_dpp v17, v34, v37 row_newbcast:0 row_mask:0xf bank_mask:0xf bound_ctrl:1
	v_fmac_f32_dpp v16, v34, v37 row_newbcast:1 row_mask:0xf bank_mask:0xf bound_ctrl:1
	v_fmac_f32_dpp v15, v34, v37 row_newbcast:2 row_mask:0xf bank_mask:0xf bound_ctrl:1
	v_fmac_f32_dpp v14, v34, v37 row_newbcast:3 row_mask:0xf bank_mask:0xf bound_ctrl:1
	v_fmac_f32_dpp v13, v34, v37 row_newbcast:4 row_mask:0xf bank_mask:0xf bound_ctrl:1
	v_fmac_f32_dpp v12, v34, v37 row_newbcast:5 row_mask:0xf bank_mask:0xf bound_ctrl:1
	v_fmac_f32_dpp v11, v34, v37 row_newbcast:6 row_mask:0xf bank_mask:0xf bound_ctrl:1
	v_fmac_f32_dpp v10, v34, v37 row_newbcast:7 row_mask:0xf bank_mask:0xf bound_ctrl:1
	v_fmac_f32_dpp v9, v34, v37 row_newbcast:8 row_mask:0xf bank_mask:0xf bound_ctrl:1
	v_fmac_f32_dpp v8, v34, v37 row_newbcast:9 row_mask:0xf bank_mask:0xf bound_ctrl:1
	v_fmac_f32_dpp v7, v34, v37 row_newbcast:10 row_mask:0xf bank_mask:0xf bound_ctrl:1
	v_fmac_f32_dpp v6, v34, v37 row_newbcast:11 row_mask:0xf bank_mask:0xf bound_ctrl:1
	v_fmac_f32_dpp v5, v34, v37 row_newbcast:12 row_mask:0xf bank_mask:0xf bound_ctrl:1
	v_fmac_f32_dpp v4, v34, v37 row_newbcast:13 row_mask:0xf bank_mask:0xf bound_ctrl:1
	v_fmac_f32_dpp v3, v34, v37 row_newbcast:14 row_mask:0xf bank_mask:0xf bound_ctrl:1
	v_fmac_f32_dpp v2, v34, v37 row_newbcast:15 row_mask:0xf bank_mask:0xf bound_ctrl:1
	v_mul_f32_dpp v24, v35, v17 row_newbcast:0 row_mask:0xf bank_mask:0xf bound_ctrl:1
	v_mul_f32_dpp v25, v35, v16 row_newbcast:1 row_mask:0xf bank_mask:0xf bound_ctrl:1
	v_fmac_f32_dpp v24, v35, v15 row_newbcast:2 row_mask:0xf bank_mask:0xf bound_ctrl:1
	v_fmac_f32_dpp v25, v35, v14 row_newbcast:3 row_mask:0xf bank_mask:0xf bound_ctrl:1
	v_fmac_f32_dpp v24, v35, v13 row_newbcast:4 row_mask:0xf bank_mask:0xf bound_ctrl:1
	v_fmac_f32_dpp v25, v35, v12 row_newbcast:5 row_mask:0xf bank_mask:0xf bound_ctrl:1
	v_fmac_f32_dpp v24, v35, v11 row_newbcast:6 row_mask:0xf bank_mask:0xf bound_ctrl:1
	v_fmac_f32_dpp v25, v35, v10 row_newbcast:7 row_mask:0xf bank_mask:0xf bound_ctrl:1
	s_nop 0
	v_fmac_f32_dpp v24, v35, v9 row_newbcast:8 row_mask:0xf bank_mask:0xf bound_ctrl:1
	v_fmac_f32_dpp v25, v35, v8 row_newbcast:9 row_mask:0xf bank_mask:0xf bound_ctrl:1
	v_fmac_f32_dpp v24, v35, v7 row_newbcast:10 row_mask:0xf bank_mask:0xf bound_ctrl:1
	v_fmac_f32_dpp v25, v35, v6 row_newbcast:11 row_mask:0xf bank_mask:0xf bound_ctrl:1
	s_nop 0
	v_fmac_f32_dpp v24, v35, v5 row_newbcast:12 row_mask:0xf bank_mask:0xf bound_ctrl:1
	v_fmac_f32_dpp v25, v35, v4 row_newbcast:13 row_mask:0xf bank_mask:0xf bound_ctrl:1
	v_fmac_f32_dpp v24, v35, v3 row_newbcast:14 row_mask:0xf bank_mask:0xf bound_ctrl:1
	v_fmac_f32_dpp v25, v35, v2 row_newbcast:15 row_mask:0xf bank_mask:0xf bound_ctrl:1
	s_waitcnt lgkmcnt(0)
	ds_read_b32 v34, v19 offset:21760
	ds_read2st64_b32 v[30:31], v21 offset0:21 offset1:37
	ds_read2st64_b32 v[32:33], v21 offset0:53 offset1:69
	v_mul_f32_dpp v35, v26, v17 row_newbcast:0 row_mask:0xf bank_mask:0xf bound_ctrl:1
	v_mul_f32_dpp v36, v26, v16 row_newbcast:1 row_mask:0xf bank_mask:0xf bound_ctrl:1
	v_fmac_f32_dpp v35, v26, v15 row_newbcast:2 row_mask:0xf bank_mask:0xf bound_ctrl:1
	v_fmac_f32_dpp v36, v26, v14 row_newbcast:3 row_mask:0xf bank_mask:0xf bound_ctrl:1
	v_fmac_f32_dpp v224, v229, v232 row_newbcast:3 row_mask:0xf bank_mask:0xf bound_ctrl:1
	v_fmac_f32_dpp v35, v26, v13 row_newbcast:4 row_mask:0xf bank_mask:0xf bound_ctrl:1
	v_fmac_f32_dpp v36, v26, v12 row_newbcast:5 row_mask:0xf bank_mask:0xf bound_ctrl:1
	v_fmac_f32_dpp v35, v26, v11 row_newbcast:6 row_mask:0xf bank_mask:0xf bound_ctrl:1
	v_fmac_f32_dpp v36, v26, v10 row_newbcast:7 row_mask:0xf bank_mask:0xf bound_ctrl:1
	v_fmac_f32_dpp v224, v230, v37 row_newbcast:3 row_mask:0xf bank_mask:0xf bound_ctrl:1
	v_fmac_f32_dpp v35, v26, v9 row_newbcast:8 row_mask:0xf bank_mask:0xf bound_ctrl:1
	v_fmac_f32_dpp v36, v26, v8 row_newbcast:9 row_mask:0xf bank_mask:0xf bound_ctrl:1
	v_fmac_f32_dpp v35, v26, v7 row_newbcast:10 row_mask:0xf bank_mask:0xf bound_ctrl:1
	v_fmac_f32_dpp v36, v26, v6 row_newbcast:11 row_mask:0xf bank_mask:0xf bound_ctrl:1
	s_nop 0
	v_fmac_f32_dpp v35, v26, v5 row_newbcast:12 row_mask:0xf bank_mask:0xf bound_ctrl:1
	v_fmac_f32_dpp v36, v26, v4 row_newbcast:13 row_mask:0xf bank_mask:0xf bound_ctrl:1
	v_fmac_f32_dpp v35, v26, v3 row_newbcast:14 row_mask:0xf bank_mask:0xf bound_ctrl:1
	v_fmac_f32_dpp v36, v26, v2 row_newbcast:15 row_mask:0xf bank_mask:0xf bound_ctrl:1
	v_fmac_f32_dpp v17, v27, v224 row_newbcast:0 row_mask:0xf bank_mask:0xf bound_ctrl:1
	v_fmac_f32_dpp v16, v27, v224 row_newbcast:1 row_mask:0xf bank_mask:0xf bound_ctrl:1
	v_fmac_f32_dpp v15, v27, v224 row_newbcast:2 row_mask:0xf bank_mask:0xf bound_ctrl:1
	v_fmac_f32_dpp v14, v27, v224 row_newbcast:3 row_mask:0xf bank_mask:0xf bound_ctrl:1
	v_fmac_f32_dpp v13, v27, v224 row_newbcast:4 row_mask:0xf bank_mask:0xf bound_ctrl:1
	v_fmac_f32_dpp v12, v27, v224 row_newbcast:5 row_mask:0xf bank_mask:0xf bound_ctrl:1
	v_fmac_f32_dpp v11, v27, v224 row_newbcast:6 row_mask:0xf bank_mask:0xf bound_ctrl:1
	v_fmac_f32_dpp v10, v27, v224 row_newbcast:7 row_mask:0xf bank_mask:0xf bound_ctrl:1
	v_fmac_f32_dpp v9, v27, v224 row_newbcast:8 row_mask:0xf bank_mask:0xf bound_ctrl:1
	v_fmac_f32_dpp v8, v27, v224 row_newbcast:9 row_mask:0xf bank_mask:0xf bound_ctrl:1
	v_fmac_f32_dpp v7, v27, v224 row_newbcast:10 row_mask:0xf bank_mask:0xf bound_ctrl:1
	v_fmac_f32_dpp v6, v27, v224 row_newbcast:11 row_mask:0xf bank_mask:0xf bound_ctrl:1
	v_fmac_f32_dpp v5, v27, v224 row_newbcast:12 row_mask:0xf bank_mask:0xf bound_ctrl:1
	v_fmac_f32_dpp v4, v27, v224 row_newbcast:13 row_mask:0xf bank_mask:0xf bound_ctrl:1
	v_fmac_f32_dpp v3, v27, v224 row_newbcast:14 row_mask:0xf bank_mask:0xf bound_ctrl:1
	v_fmac_f32_dpp v2, v27, v224 row_newbcast:15 row_mask:0xf bank_mask:0xf bound_ctrl:1
	s_nop 0
	v_add_f32 v35, v35, v36
	s_nop 0
	s_nop 0
	v_mfma_f32_16x16x4_f32 v[232:235], v228, v35, 0
	ds_write_b64 v22, v[24:25] offset:55296
	v_fmac_f32_dpp v17, v28, v40 row_newbcast:0 row_mask:0xf bank_mask:0xf bound_ctrl:1
	v_fmac_f32_dpp v16, v28, v40 row_newbcast:1 row_mask:0xf bank_mask:0xf bound_ctrl:1
	v_fmac_f32_dpp v15, v28, v40 row_newbcast:2 row_mask:0xf bank_mask:0xf bound_ctrl:1
	v_fmac_f32_dpp v14, v28, v40 row_newbcast:3 row_mask:0xf bank_mask:0xf bound_ctrl:1
	v_fmac_f32_dpp v13, v28, v40 row_newbcast:4 row_mask:0xf bank_mask:0xf bound_ctrl:1
	v_fmac_f32_dpp v12, v28, v40 row_newbcast:5 row_mask:0xf bank_mask:0xf bound_ctrl:1
	v_fmac_f32_dpp v11, v28, v40 row_newbcast:6 row_mask:0xf bank_mask:0xf bound_ctrl:1
	v_fmac_f32_dpp v10, v28, v40 row_newbcast:7 row_mask:0xf bank_mask:0xf bound_ctrl:1
	v_fmac_f32_dpp v9, v28, v40 row_newbcast:8 row_mask:0xf bank_mask:0xf bound_ctrl:1
	v_fmac_f32_dpp v8, v28, v40 row_newbcast:9 row_mask:0xf bank_mask:0xf bound_ctrl:1
	v_fmac_f32_dpp v7, v28, v40 row_newbcast:10 row_mask:0xf bank_mask:0xf bound_ctrl:1
	v_fmac_f32_dpp v6, v28, v40 row_newbcast:11 row_mask:0xf bank_mask:0xf bound_ctrl:1
	v_fmac_f32_dpp v5, v28, v40 row_newbcast:12 row_mask:0xf bank_mask:0xf bound_ctrl:1
	v_fmac_f32_dpp v4, v28, v40 row_newbcast:13 row_mask:0xf bank_mask:0xf bound_ctrl:1
	v_fmac_f32_dpp v3, v28, v40 row_newbcast:14 row_mask:0xf bank_mask:0xf bound_ctrl:1
	v_fmac_f32_dpp v2, v28, v40 row_newbcast:15 row_mask:0xf bank_mask:0xf bound_ctrl:1
	v_mul_f32_dpp v24, v29, v17 row_newbcast:0 row_mask:0xf bank_mask:0xf bound_ctrl:1
	v_mul_f32_dpp v25, v29, v16 row_newbcast:1 row_mask:0xf bank_mask:0xf bound_ctrl:1
	v_fmac_f32_dpp v24, v29, v15 row_newbcast:2 row_mask:0xf bank_mask:0xf bound_ctrl:1
	v_fmac_f32_dpp v25, v29, v14 row_newbcast:3 row_mask:0xf bank_mask:0xf bound_ctrl:1
	v_fmac_f32_dpp v24, v29, v13 row_newbcast:4 row_mask:0xf bank_mask:0xf bound_ctrl:1
	v_fmac_f32_dpp v25, v29, v12 row_newbcast:5 row_mask:0xf bank_mask:0xf bound_ctrl:1
	v_fmac_f32_dpp v24, v29, v11 row_newbcast:6 row_mask:0xf bank_mask:0xf bound_ctrl:1
	v_fmac_f32_dpp v25, v29, v10 row_newbcast:7 row_mask:0xf bank_mask:0xf bound_ctrl:1
	s_nop 0
	v_fmac_f32_dpp v24, v29, v9 row_newbcast:8 row_mask:0xf bank_mask:0xf bound_ctrl:1
	v_fmac_f32_dpp v25, v29, v8 row_newbcast:9 row_mask:0xf bank_mask:0xf bound_ctrl:1
	v_fmac_f32_dpp v24, v29, v7 row_newbcast:10 row_mask:0xf bank_mask:0xf bound_ctrl:1
	v_fmac_f32_dpp v25, v29, v6 row_newbcast:11 row_mask:0xf bank_mask:0xf bound_ctrl:1
	s_nop 0
	v_fmac_f32_dpp v24, v29, v5 row_newbcast:12 row_mask:0xf bank_mask:0xf bound_ctrl:1
	v_fmac_f32_dpp v25, v29, v4 row_newbcast:13 row_mask:0xf bank_mask:0xf bound_ctrl:1
	v_fmac_f32_dpp v24, v29, v3 row_newbcast:14 row_mask:0xf bank_mask:0xf bound_ctrl:1
	v_fmac_f32_dpp v25, v29, v2 row_newbcast:15 row_mask:0xf bank_mask:0xf bound_ctrl:1
	s_waitcnt lgkmcnt(0)
	ds_read_b32 v36, v19 offset:22016
	ds_read2st64_b32 v[26:27], v21 offset0:22 offset1:38
	ds_read2st64_b32 v[28:29], v21 offset0:54 offset1:70
	v_mul_f32_dpp v37, v30, v17 row_newbcast:0 row_mask:0xf bank_mask:0xf bound_ctrl:1
	v_mul_f32_dpp v38, v30, v16 row_newbcast:1 row_mask:0xf bank_mask:0xf bound_ctrl:1
	v_fmac_f32_dpp v37, v30, v15 row_newbcast:2 row_mask:0xf bank_mask:0xf bound_ctrl:1
	v_fmac_f32_dpp v38, v30, v14 row_newbcast:3 row_mask:0xf bank_mask:0xf bound_ctrl:1
	v_fmac_f32_dpp v232, v229, v224 row_newbcast:4 row_mask:0xf bank_mask:0xf bound_ctrl:1
	v_fmac_f32_dpp v37, v30, v13 row_newbcast:4 row_mask:0xf bank_mask:0xf bound_ctrl:1
	v_fmac_f32_dpp v38, v30, v12 row_newbcast:5 row_mask:0xf bank_mask:0xf bound_ctrl:1
	v_fmac_f32_dpp v37, v30, v11 row_newbcast:6 row_mask:0xf bank_mask:0xf bound_ctrl:1
	v_fmac_f32_dpp v38, v30, v10 row_newbcast:7 row_mask:0xf bank_mask:0xf bound_ctrl:1
	v_fmac_f32_dpp v232, v230, v40 row_newbcast:4 row_mask:0xf bank_mask:0xf bound_ctrl:1
	v_fmac_f32_dpp v37, v30, v9 row_newbcast:8 row_mask:0xf bank_mask:0xf bound_ctrl:1
	v_fmac_f32_dpp v38, v30, v8 row_newbcast:9 row_mask:0xf bank_mask:0xf bound_ctrl:1
	v_fmac_f32_dpp v37, v30, v7 row_newbcast:10 row_mask:0xf bank_mask:0xf bound_ctrl:1
	v_fmac_f32_dpp v38, v30, v6 row_newbcast:11 row_mask:0xf bank_mask:0xf bound_ctrl:1
	s_nop 0
	v_fmac_f32_dpp v37, v30, v5 row_newbcast:12 row_mask:0xf bank_mask:0xf bound_ctrl:1
	v_fmac_f32_dpp v38, v30, v4 row_newbcast:13 row_mask:0xf bank_mask:0xf bound_ctrl:1
	v_fmac_f32_dpp v37, v30, v3 row_newbcast:14 row_mask:0xf bank_mask:0xf bound_ctrl:1
	v_fmac_f32_dpp v38, v30, v2 row_newbcast:15 row_mask:0xf bank_mask:0xf bound_ctrl:1
	v_fmac_f32_dpp v17, v31, v232 row_newbcast:0 row_mask:0xf bank_mask:0xf bound_ctrl:1
	v_fmac_f32_dpp v16, v31, v232 row_newbcast:1 row_mask:0xf bank_mask:0xf bound_ctrl:1
	v_fmac_f32_dpp v15, v31, v232 row_newbcast:2 row_mask:0xf bank_mask:0xf bound_ctrl:1
	v_fmac_f32_dpp v14, v31, v232 row_newbcast:3 row_mask:0xf bank_mask:0xf bound_ctrl:1
	v_fmac_f32_dpp v13, v31, v232 row_newbcast:4 row_mask:0xf bank_mask:0xf bound_ctrl:1
	v_fmac_f32_dpp v12, v31, v232 row_newbcast:5 row_mask:0xf bank_mask:0xf bound_ctrl:1
	v_fmac_f32_dpp v11, v31, v232 row_newbcast:6 row_mask:0xf bank_mask:0xf bound_ctrl:1
	v_fmac_f32_dpp v10, v31, v232 row_newbcast:7 row_mask:0xf bank_mask:0xf bound_ctrl:1
	v_fmac_f32_dpp v9, v31, v232 row_newbcast:8 row_mask:0xf bank_mask:0xf bound_ctrl:1
	v_fmac_f32_dpp v8, v31, v232 row_newbcast:9 row_mask:0xf bank_mask:0xf bound_ctrl:1
	v_fmac_f32_dpp v7, v31, v232 row_newbcast:10 row_mask:0xf bank_mask:0xf bound_ctrl:1
	v_fmac_f32_dpp v6, v31, v232 row_newbcast:11 row_mask:0xf bank_mask:0xf bound_ctrl:1
	v_fmac_f32_dpp v5, v31, v232 row_newbcast:12 row_mask:0xf bank_mask:0xf bound_ctrl:1
	v_fmac_f32_dpp v4, v31, v232 row_newbcast:13 row_mask:0xf bank_mask:0xf bound_ctrl:1
	v_fmac_f32_dpp v3, v31, v232 row_newbcast:14 row_mask:0xf bank_mask:0xf bound_ctrl:1
	v_fmac_f32_dpp v2, v31, v232 row_newbcast:15 row_mask:0xf bank_mask:0xf bound_ctrl:1
	s_nop 0
	v_add_f32 v37, v37, v38
	s_nop 0
	s_nop 0
	v_mfma_f32_16x16x4_f32 v[224:227], v228, v37, 0
	ds_write_b64 v22, v[24:25] offset:57344
	v_fmac_f32_dpp v17, v32, v34 row_newbcast:0 row_mask:0xf bank_mask:0xf bound_ctrl:1
	v_fmac_f32_dpp v16, v32, v34 row_newbcast:1 row_mask:0xf bank_mask:0xf bound_ctrl:1
	v_fmac_f32_dpp v15, v32, v34 row_newbcast:2 row_mask:0xf bank_mask:0xf bound_ctrl:1
	v_fmac_f32_dpp v14, v32, v34 row_newbcast:3 row_mask:0xf bank_mask:0xf bound_ctrl:1
	v_fmac_f32_dpp v13, v32, v34 row_newbcast:4 row_mask:0xf bank_mask:0xf bound_ctrl:1
	v_fmac_f32_dpp v12, v32, v34 row_newbcast:5 row_mask:0xf bank_mask:0xf bound_ctrl:1
	v_fmac_f32_dpp v11, v32, v34 row_newbcast:6 row_mask:0xf bank_mask:0xf bound_ctrl:1
	v_fmac_f32_dpp v10, v32, v34 row_newbcast:7 row_mask:0xf bank_mask:0xf bound_ctrl:1
	v_fmac_f32_dpp v9, v32, v34 row_newbcast:8 row_mask:0xf bank_mask:0xf bound_ctrl:1
	v_fmac_f32_dpp v8, v32, v34 row_newbcast:9 row_mask:0xf bank_mask:0xf bound_ctrl:1
	v_fmac_f32_dpp v7, v32, v34 row_newbcast:10 row_mask:0xf bank_mask:0xf bound_ctrl:1
	v_fmac_f32_dpp v6, v32, v34 row_newbcast:11 row_mask:0xf bank_mask:0xf bound_ctrl:1
	v_fmac_f32_dpp v5, v32, v34 row_newbcast:12 row_mask:0xf bank_mask:0xf bound_ctrl:1
	v_fmac_f32_dpp v4, v32, v34 row_newbcast:13 row_mask:0xf bank_mask:0xf bound_ctrl:1
	v_fmac_f32_dpp v3, v32, v34 row_newbcast:14 row_mask:0xf bank_mask:0xf bound_ctrl:1
	v_fmac_f32_dpp v2, v32, v34 row_newbcast:15 row_mask:0xf bank_mask:0xf bound_ctrl:1
	v_mul_f32_dpp v24, v33, v17 row_newbcast:0 row_mask:0xf bank_mask:0xf bound_ctrl:1
	v_mul_f32_dpp v25, v33, v16 row_newbcast:1 row_mask:0xf bank_mask:0xf bound_ctrl:1
	v_fmac_f32_dpp v24, v33, v15 row_newbcast:2 row_mask:0xf bank_mask:0xf bound_ctrl:1
	v_fmac_f32_dpp v25, v33, v14 row_newbcast:3 row_mask:0xf bank_mask:0xf bound_ctrl:1
	v_fmac_f32_dpp v24, v33, v13 row_newbcast:4 row_mask:0xf bank_mask:0xf bound_ctrl:1
	v_fmac_f32_dpp v25, v33, v12 row_newbcast:5 row_mask:0xf bank_mask:0xf bound_ctrl:1
	v_fmac_f32_dpp v24, v33, v11 row_newbcast:6 row_mask:0xf bank_mask:0xf bound_ctrl:1
	v_fmac_f32_dpp v25, v33, v10 row_newbcast:7 row_mask:0xf bank_mask:0xf bound_ctrl:1
	s_nop 0
	v_fmac_f32_dpp v24, v33, v9 row_newbcast:8 row_mask:0xf bank_mask:0xf bound_ctrl:1
	v_fmac_f32_dpp v25, v33, v8 row_newbcast:9 row_mask:0xf bank_mask:0xf bound_ctrl:1
	v_fmac_f32_dpp v24, v33, v7 row_newbcast:10 row_mask:0xf bank_mask:0xf bound_ctrl:1
	v_fmac_f32_dpp v25, v33, v6 row_newbcast:11 row_mask:0xf bank_mask:0xf bound_ctrl:1
	s_nop 0
	v_fmac_f32_dpp v24, v33, v5 row_newbcast:12 row_mask:0xf bank_mask:0xf bound_ctrl:1
	v_fmac_f32_dpp v25, v33, v4 row_newbcast:13 row_mask:0xf bank_mask:0xf bound_ctrl:1
	v_fmac_f32_dpp v24, v33, v3 row_newbcast:14 row_mask:0xf bank_mask:0xf bound_ctrl:1
	v_fmac_f32_dpp v25, v33, v2 row_newbcast:15 row_mask:0xf bank_mask:0xf bound_ctrl:1
	s_waitcnt lgkmcnt(0)
	ds_read_b32 v38, v19 offset:22272
	ds_read2st64_b32 v[30:31], v21 offset0:23 offset1:39
	ds_read2st64_b32 v[32:33], v21 offset0:55 offset1:71
	v_mul_f32_dpp v39, v26, v17 row_newbcast:0 row_mask:0xf bank_mask:0xf bound_ctrl:1
	v_mul_f32_dpp v40, v26, v16 row_newbcast:1 row_mask:0xf bank_mask:0xf bound_ctrl:1
	v_fmac_f32_dpp v39, v26, v15 row_newbcast:2 row_mask:0xf bank_mask:0xf bound_ctrl:1
	v_fmac_f32_dpp v40, v26, v14 row_newbcast:3 row_mask:0xf bank_mask:0xf bound_ctrl:1
	v_fmac_f32_dpp v224, v229, v232 row_newbcast:5 row_mask:0xf bank_mask:0xf bound_ctrl:1
	v_fmac_f32_dpp v39, v26, v13 row_newbcast:4 row_mask:0xf bank_mask:0xf bound_ctrl:1
	v_fmac_f32_dpp v40, v26, v12 row_newbcast:5 row_mask:0xf bank_mask:0xf bound_ctrl:1
	v_fmac_f32_dpp v39, v26, v11 row_newbcast:6 row_mask:0xf bank_mask:0xf bound_ctrl:1
	v_fmac_f32_dpp v40, v26, v10 row_newbcast:7 row_mask:0xf bank_mask:0xf bound_ctrl:1
	v_fmac_f32_dpp v224, v230, v34 row_newbcast:5 row_mask:0xf bank_mask:0xf bound_ctrl:1
	v_fmac_f32_dpp v39, v26, v9 row_newbcast:8 row_mask:0xf bank_mask:0xf bound_ctrl:1
	v_fmac_f32_dpp v40, v26, v8 row_newbcast:9 row_mask:0xf bank_mask:0xf bound_ctrl:1
	v_fmac_f32_dpp v39, v26, v7 row_newbcast:10 row_mask:0xf bank_mask:0xf bound_ctrl:1
	v_fmac_f32_dpp v40, v26, v6 row_newbcast:11 row_mask:0xf bank_mask:0xf bound_ctrl:1
	s_nop 0
	v_fmac_f32_dpp v39, v26, v5 row_newbcast:12 row_mask:0xf bank_mask:0xf bound_ctrl:1
	v_fmac_f32_dpp v40, v26, v4 row_newbcast:13 row_mask:0xf bank_mask:0xf bound_ctrl:1
	v_fmac_f32_dpp v39, v26, v3 row_newbcast:14 row_mask:0xf bank_mask:0xf bound_ctrl:1
	v_fmac_f32_dpp v40, v26, v2 row_newbcast:15 row_mask:0xf bank_mask:0xf bound_ctrl:1
	v_fmac_f32_dpp v17, v27, v224 row_newbcast:0 row_mask:0xf bank_mask:0xf bound_ctrl:1
	v_fmac_f32_dpp v16, v27, v224 row_newbcast:1 row_mask:0xf bank_mask:0xf bound_ctrl:1
	v_fmac_f32_dpp v15, v27, v224 row_newbcast:2 row_mask:0xf bank_mask:0xf bound_ctrl:1
	v_fmac_f32_dpp v14, v27, v224 row_newbcast:3 row_mask:0xf bank_mask:0xf bound_ctrl:1
	v_fmac_f32_dpp v13, v27, v224 row_newbcast:4 row_mask:0xf bank_mask:0xf bound_ctrl:1
	v_fmac_f32_dpp v12, v27, v224 row_newbcast:5 row_mask:0xf bank_mask:0xf bound_ctrl:1
	v_fmac_f32_dpp v11, v27, v224 row_newbcast:6 row_mask:0xf bank_mask:0xf bound_ctrl:1
	v_fmac_f32_dpp v10, v27, v224 row_newbcast:7 row_mask:0xf bank_mask:0xf bound_ctrl:1
	v_fmac_f32_dpp v9, v27, v224 row_newbcast:8 row_mask:0xf bank_mask:0xf bound_ctrl:1
	v_fmac_f32_dpp v8, v27, v224 row_newbcast:9 row_mask:0xf bank_mask:0xf bound_ctrl:1
	v_fmac_f32_dpp v7, v27, v224 row_newbcast:10 row_mask:0xf bank_mask:0xf bound_ctrl:1
	v_fmac_f32_dpp v6, v27, v224 row_newbcast:11 row_mask:0xf bank_mask:0xf bound_ctrl:1
	v_fmac_f32_dpp v5, v27, v224 row_newbcast:12 row_mask:0xf bank_mask:0xf bound_ctrl:1
	v_fmac_f32_dpp v4, v27, v224 row_newbcast:13 row_mask:0xf bank_mask:0xf bound_ctrl:1
	v_fmac_f32_dpp v3, v27, v224 row_newbcast:14 row_mask:0xf bank_mask:0xf bound_ctrl:1
	v_fmac_f32_dpp v2, v27, v224 row_newbcast:15 row_mask:0xf bank_mask:0xf bound_ctrl:1
	s_nop 0
	v_add_f32 v39, v39, v40
	s_nop 0
	s_nop 0
	v_mfma_f32_16x16x4_f32 v[232:235], v228, v39, 0
	ds_write_b64 v22, v[24:25] offset:59392
	v_fmac_f32_dpp v17, v28, v36 row_newbcast:0 row_mask:0xf bank_mask:0xf bound_ctrl:1
	v_fmac_f32_dpp v16, v28, v36 row_newbcast:1 row_mask:0xf bank_mask:0xf bound_ctrl:1
	v_fmac_f32_dpp v15, v28, v36 row_newbcast:2 row_mask:0xf bank_mask:0xf bound_ctrl:1
	v_fmac_f32_dpp v14, v28, v36 row_newbcast:3 row_mask:0xf bank_mask:0xf bound_ctrl:1
	v_fmac_f32_dpp v13, v28, v36 row_newbcast:4 row_mask:0xf bank_mask:0xf bound_ctrl:1
	v_fmac_f32_dpp v12, v28, v36 row_newbcast:5 row_mask:0xf bank_mask:0xf bound_ctrl:1
	v_fmac_f32_dpp v11, v28, v36 row_newbcast:6 row_mask:0xf bank_mask:0xf bound_ctrl:1
	v_fmac_f32_dpp v10, v28, v36 row_newbcast:7 row_mask:0xf bank_mask:0xf bound_ctrl:1
	v_fmac_f32_dpp v9, v28, v36 row_newbcast:8 row_mask:0xf bank_mask:0xf bound_ctrl:1
	v_fmac_f32_dpp v8, v28, v36 row_newbcast:9 row_mask:0xf bank_mask:0xf bound_ctrl:1
	v_fmac_f32_dpp v7, v28, v36 row_newbcast:10 row_mask:0xf bank_mask:0xf bound_ctrl:1
	v_fmac_f32_dpp v6, v28, v36 row_newbcast:11 row_mask:0xf bank_mask:0xf bound_ctrl:1
	v_fmac_f32_dpp v5, v28, v36 row_newbcast:12 row_mask:0xf bank_mask:0xf bound_ctrl:1
	v_fmac_f32_dpp v4, v28, v36 row_newbcast:13 row_mask:0xf bank_mask:0xf bound_ctrl:1
	v_fmac_f32_dpp v3, v28, v36 row_newbcast:14 row_mask:0xf bank_mask:0xf bound_ctrl:1
	v_fmac_f32_dpp v2, v28, v36 row_newbcast:15 row_mask:0xf bank_mask:0xf bound_ctrl:1
	v_mul_f32_dpp v24, v29, v17 row_newbcast:0 row_mask:0xf bank_mask:0xf bound_ctrl:1
	v_mul_f32_dpp v25, v29, v16 row_newbcast:1 row_mask:0xf bank_mask:0xf bound_ctrl:1
	v_fmac_f32_dpp v24, v29, v15 row_newbcast:2 row_mask:0xf bank_mask:0xf bound_ctrl:1
	v_fmac_f32_dpp v25, v29, v14 row_newbcast:3 row_mask:0xf bank_mask:0xf bound_ctrl:1
	v_fmac_f32_dpp v24, v29, v13 row_newbcast:4 row_mask:0xf bank_mask:0xf bound_ctrl:1
	v_fmac_f32_dpp v25, v29, v12 row_newbcast:5 row_mask:0xf bank_mask:0xf bound_ctrl:1
	v_fmac_f32_dpp v24, v29, v11 row_newbcast:6 row_mask:0xf bank_mask:0xf bound_ctrl:1
	v_fmac_f32_dpp v25, v29, v10 row_newbcast:7 row_mask:0xf bank_mask:0xf bound_ctrl:1
	s_nop 0
	v_fmac_f32_dpp v24, v29, v9 row_newbcast:8 row_mask:0xf bank_mask:0xf bound_ctrl:1
	v_fmac_f32_dpp v25, v29, v8 row_newbcast:9 row_mask:0xf bank_mask:0xf bound_ctrl:1
	v_fmac_f32_dpp v24, v29, v7 row_newbcast:10 row_mask:0xf bank_mask:0xf bound_ctrl:1
	v_fmac_f32_dpp v25, v29, v6 row_newbcast:11 row_mask:0xf bank_mask:0xf bound_ctrl:1
	s_nop 0
	v_fmac_f32_dpp v24, v29, v5 row_newbcast:12 row_mask:0xf bank_mask:0xf bound_ctrl:1
	v_fmac_f32_dpp v25, v29, v4 row_newbcast:13 row_mask:0xf bank_mask:0xf bound_ctrl:1
	v_fmac_f32_dpp v24, v29, v3 row_newbcast:14 row_mask:0xf bank_mask:0xf bound_ctrl:1
	v_fmac_f32_dpp v25, v29, v2 row_newbcast:15 row_mask:0xf bank_mask:0xf bound_ctrl:1
	s_waitcnt lgkmcnt(0)
	ds_read_b32 v34, v19 offset:22528
	ds_read2st64_b32 v[26:27], v21 offset0:24 offset1:40
	ds_read2st64_b32 v[28:29], v21 offset0:56 offset1:72
	v_mul_f32_dpp v35, v30, v17 row_newbcast:0 row_mask:0xf bank_mask:0xf bound_ctrl:1
	v_mul_f32_dpp v40, v30, v16 row_newbcast:1 row_mask:0xf bank_mask:0xf bound_ctrl:1
	v_fmac_f32_dpp v35, v30, v15 row_newbcast:2 row_mask:0xf bank_mask:0xf bound_ctrl:1
	v_fmac_f32_dpp v40, v30, v14 row_newbcast:3 row_mask:0xf bank_mask:0xf bound_ctrl:1
	v_fmac_f32_dpp v232, v229, v224 row_newbcast:6 row_mask:0xf bank_mask:0xf bound_ctrl:1
	v_fmac_f32_dpp v35, v30, v13 row_newbcast:4 row_mask:0xf bank_mask:0xf bound_ctrl:1
	v_fmac_f32_dpp v40, v30, v12 row_newbcast:5 row_mask:0xf bank_mask:0xf bound_ctrl:1
	v_fmac_f32_dpp v35, v30, v11 row_newbcast:6 row_mask:0xf bank_mask:0xf bound_ctrl:1
	v_fmac_f32_dpp v40, v30, v10 row_newbcast:7 row_mask:0xf bank_mask:0xf bound_ctrl:1
	v_fmac_f32_dpp v232, v230, v36 row_newbcast:6 row_mask:0xf bank_mask:0xf bound_ctrl:1
	v_fmac_f32_dpp v35, v30, v9 row_newbcast:8 row_mask:0xf bank_mask:0xf bound_ctrl:1
	v_fmac_f32_dpp v40, v30, v8 row_newbcast:9 row_mask:0xf bank_mask:0xf bound_ctrl:1
	v_fmac_f32_dpp v35, v30, v7 row_newbcast:10 row_mask:0xf bank_mask:0xf bound_ctrl:1
	v_fmac_f32_dpp v40, v30, v6 row_newbcast:11 row_mask:0xf bank_mask:0xf bound_ctrl:1
	s_nop 0
	v_fmac_f32_dpp v35, v30, v5 row_newbcast:12 row_mask:0xf bank_mask:0xf bound_ctrl:1
	v_fmac_f32_dpp v40, v30, v4 row_newbcast:13 row_mask:0xf bank_mask:0xf bound_ctrl:1
	v_fmac_f32_dpp v35, v30, v3 row_newbcast:14 row_mask:0xf bank_mask:0xf bound_ctrl:1
	v_fmac_f32_dpp v40, v30, v2 row_newbcast:15 row_mask:0xf bank_mask:0xf bound_ctrl:1
	v_fmac_f32_dpp v17, v31, v232 row_newbcast:0 row_mask:0xf bank_mask:0xf bound_ctrl:1
	v_fmac_f32_dpp v16, v31, v232 row_newbcast:1 row_mask:0xf bank_mask:0xf bound_ctrl:1
	v_fmac_f32_dpp v15, v31, v232 row_newbcast:2 row_mask:0xf bank_mask:0xf bound_ctrl:1
	v_fmac_f32_dpp v14, v31, v232 row_newbcast:3 row_mask:0xf bank_mask:0xf bound_ctrl:1
	v_fmac_f32_dpp v13, v31, v232 row_newbcast:4 row_mask:0xf bank_mask:0xf bound_ctrl:1
	v_fmac_f32_dpp v12, v31, v232 row_newbcast:5 row_mask:0xf bank_mask:0xf bound_ctrl:1
	v_fmac_f32_dpp v11, v31, v232 row_newbcast:6 row_mask:0xf bank_mask:0xf bound_ctrl:1
	v_fmac_f32_dpp v10, v31, v232 row_newbcast:7 row_mask:0xf bank_mask:0xf bound_ctrl:1
	v_fmac_f32_dpp v9, v31, v232 row_newbcast:8 row_mask:0xf bank_mask:0xf bound_ctrl:1
	v_fmac_f32_dpp v8, v31, v232 row_newbcast:9 row_mask:0xf bank_mask:0xf bound_ctrl:1
	v_fmac_f32_dpp v7, v31, v232 row_newbcast:10 row_mask:0xf bank_mask:0xf bound_ctrl:1
	v_fmac_f32_dpp v6, v31, v232 row_newbcast:11 row_mask:0xf bank_mask:0xf bound_ctrl:1
	v_fmac_f32_dpp v5, v31, v232 row_newbcast:12 row_mask:0xf bank_mask:0xf bound_ctrl:1
	v_fmac_f32_dpp v4, v31, v232 row_newbcast:13 row_mask:0xf bank_mask:0xf bound_ctrl:1
	v_fmac_f32_dpp v3, v31, v232 row_newbcast:14 row_mask:0xf bank_mask:0xf bound_ctrl:1
	v_fmac_f32_dpp v2, v31, v232 row_newbcast:15 row_mask:0xf bank_mask:0xf bound_ctrl:1
	s_nop 0
	v_add_f32 v35, v35, v40
	s_nop 0
	s_nop 0
	v_mfma_f32_16x16x4_f32 v[224:227], v228, v35, 0
	ds_write_b64 v22, v[24:25] offset:61440
	v_fmac_f32_dpp v17, v32, v38 row_newbcast:0 row_mask:0xf bank_mask:0xf bound_ctrl:1
	v_fmac_f32_dpp v16, v32, v38 row_newbcast:1 row_mask:0xf bank_mask:0xf bound_ctrl:1
	v_fmac_f32_dpp v15, v32, v38 row_newbcast:2 row_mask:0xf bank_mask:0xf bound_ctrl:1
	v_fmac_f32_dpp v14, v32, v38 row_newbcast:3 row_mask:0xf bank_mask:0xf bound_ctrl:1
	v_fmac_f32_dpp v13, v32, v38 row_newbcast:4 row_mask:0xf bank_mask:0xf bound_ctrl:1
	v_fmac_f32_dpp v12, v32, v38 row_newbcast:5 row_mask:0xf bank_mask:0xf bound_ctrl:1
	v_fmac_f32_dpp v11, v32, v38 row_newbcast:6 row_mask:0xf bank_mask:0xf bound_ctrl:1
	v_fmac_f32_dpp v10, v32, v38 row_newbcast:7 row_mask:0xf bank_mask:0xf bound_ctrl:1
	v_fmac_f32_dpp v9, v32, v38 row_newbcast:8 row_mask:0xf bank_mask:0xf bound_ctrl:1
	v_fmac_f32_dpp v8, v32, v38 row_newbcast:9 row_mask:0xf bank_mask:0xf bound_ctrl:1
	v_fmac_f32_dpp v7, v32, v38 row_newbcast:10 row_mask:0xf bank_mask:0xf bound_ctrl:1
	v_fmac_f32_dpp v6, v32, v38 row_newbcast:11 row_mask:0xf bank_mask:0xf bound_ctrl:1
	v_fmac_f32_dpp v5, v32, v38 row_newbcast:12 row_mask:0xf bank_mask:0xf bound_ctrl:1
	v_fmac_f32_dpp v4, v32, v38 row_newbcast:13 row_mask:0xf bank_mask:0xf bound_ctrl:1
	v_fmac_f32_dpp v3, v32, v38 row_newbcast:14 row_mask:0xf bank_mask:0xf bound_ctrl:1
	v_fmac_f32_dpp v2, v32, v38 row_newbcast:15 row_mask:0xf bank_mask:0xf bound_ctrl:1
	v_mul_f32_dpp v24, v33, v17 row_newbcast:0 row_mask:0xf bank_mask:0xf bound_ctrl:1
	v_mul_f32_dpp v25, v33, v16 row_newbcast:1 row_mask:0xf bank_mask:0xf bound_ctrl:1
	v_fmac_f32_dpp v24, v33, v15 row_newbcast:2 row_mask:0xf bank_mask:0xf bound_ctrl:1
	v_fmac_f32_dpp v25, v33, v14 row_newbcast:3 row_mask:0xf bank_mask:0xf bound_ctrl:1
	v_fmac_f32_dpp v24, v33, v13 row_newbcast:4 row_mask:0xf bank_mask:0xf bound_ctrl:1
	v_fmac_f32_dpp v25, v33, v12 row_newbcast:5 row_mask:0xf bank_mask:0xf bound_ctrl:1
	v_fmac_f32_dpp v24, v33, v11 row_newbcast:6 row_mask:0xf bank_mask:0xf bound_ctrl:1
	v_fmac_f32_dpp v25, v33, v10 row_newbcast:7 row_mask:0xf bank_mask:0xf bound_ctrl:1
	s_nop 0
	v_fmac_f32_dpp v24, v33, v9 row_newbcast:8 row_mask:0xf bank_mask:0xf bound_ctrl:1
	v_fmac_f32_dpp v25, v33, v8 row_newbcast:9 row_mask:0xf bank_mask:0xf bound_ctrl:1
	v_fmac_f32_dpp v24, v33, v7 row_newbcast:10 row_mask:0xf bank_mask:0xf bound_ctrl:1
	v_fmac_f32_dpp v25, v33, v6 row_newbcast:11 row_mask:0xf bank_mask:0xf bound_ctrl:1
	s_nop 0
	v_fmac_f32_dpp v24, v33, v5 row_newbcast:12 row_mask:0xf bank_mask:0xf bound_ctrl:1
	v_fmac_f32_dpp v25, v33, v4 row_newbcast:13 row_mask:0xf bank_mask:0xf bound_ctrl:1
	v_fmac_f32_dpp v24, v33, v3 row_newbcast:14 row_mask:0xf bank_mask:0xf bound_ctrl:1
	v_fmac_f32_dpp v25, v33, v2 row_newbcast:15 row_mask:0xf bank_mask:0xf bound_ctrl:1
	s_waitcnt lgkmcnt(0)
	ds_read_b32 v36, v19 offset:22784
	ds_read2st64_b32 v[30:31], v21 offset0:25 offset1:41
	ds_read2st64_b32 v[32:33], v21 offset0:57 offset1:73
	v_mul_f32_dpp v37, v26, v17 row_newbcast:0 row_mask:0xf bank_mask:0xf bound_ctrl:1
	v_mul_f32_dpp v40, v26, v16 row_newbcast:1 row_mask:0xf bank_mask:0xf bound_ctrl:1
	v_fmac_f32_dpp v37, v26, v15 row_newbcast:2 row_mask:0xf bank_mask:0xf bound_ctrl:1
	v_fmac_f32_dpp v40, v26, v14 row_newbcast:3 row_mask:0xf bank_mask:0xf bound_ctrl:1
	v_fmac_f32_dpp v224, v229, v232 row_newbcast:7 row_mask:0xf bank_mask:0xf bound_ctrl:1
	v_fmac_f32_dpp v37, v26, v13 row_newbcast:4 row_mask:0xf bank_mask:0xf bound_ctrl:1
	v_fmac_f32_dpp v40, v26, v12 row_newbcast:5 row_mask:0xf bank_mask:0xf bound_ctrl:1
	v_fmac_f32_dpp v37, v26, v11 row_newbcast:6 row_mask:0xf bank_mask:0xf bound_ctrl:1
	v_fmac_f32_dpp v40, v26, v10 row_newbcast:7 row_mask:0xf bank_mask:0xf bound_ctrl:1
	v_fmac_f32_dpp v224, v230, v38 row_newbcast:7 row_mask:0xf bank_mask:0xf bound_ctrl:1
	v_fmac_f32_dpp v37, v26, v9 row_newbcast:8 row_mask:0xf bank_mask:0xf bound_ctrl:1
	v_fmac_f32_dpp v40, v26, v8 row_newbcast:9 row_mask:0xf bank_mask:0xf bound_ctrl:1
	v_fmac_f32_dpp v37, v26, v7 row_newbcast:10 row_mask:0xf bank_mask:0xf bound_ctrl:1
	v_fmac_f32_dpp v40, v26, v6 row_newbcast:11 row_mask:0xf bank_mask:0xf bound_ctrl:1
	s_nop 0
	v_fmac_f32_dpp v37, v26, v5 row_newbcast:12 row_mask:0xf bank_mask:0xf bound_ctrl:1
	v_fmac_f32_dpp v40, v26, v4 row_newbcast:13 row_mask:0xf bank_mask:0xf bound_ctrl:1
	v_fmac_f32_dpp v37, v26, v3 row_newbcast:14 row_mask:0xf bank_mask:0xf bound_ctrl:1
	v_fmac_f32_dpp v40, v26, v2 row_newbcast:15 row_mask:0xf bank_mask:0xf bound_ctrl:1
	v_fmac_f32_dpp v17, v27, v224 row_newbcast:0 row_mask:0xf bank_mask:0xf bound_ctrl:1
	v_fmac_f32_dpp v16, v27, v224 row_newbcast:1 row_mask:0xf bank_mask:0xf bound_ctrl:1
	v_fmac_f32_dpp v15, v27, v224 row_newbcast:2 row_mask:0xf bank_mask:0xf bound_ctrl:1
	v_fmac_f32_dpp v14, v27, v224 row_newbcast:3 row_mask:0xf bank_mask:0xf bound_ctrl:1
	v_fmac_f32_dpp v13, v27, v224 row_newbcast:4 row_mask:0xf bank_mask:0xf bound_ctrl:1
	v_fmac_f32_dpp v12, v27, v224 row_newbcast:5 row_mask:0xf bank_mask:0xf bound_ctrl:1
	v_fmac_f32_dpp v11, v27, v224 row_newbcast:6 row_mask:0xf bank_mask:0xf bound_ctrl:1
	v_fmac_f32_dpp v10, v27, v224 row_newbcast:7 row_mask:0xf bank_mask:0xf bound_ctrl:1
	v_fmac_f32_dpp v9, v27, v224 row_newbcast:8 row_mask:0xf bank_mask:0xf bound_ctrl:1
	v_fmac_f32_dpp v8, v27, v224 row_newbcast:9 row_mask:0xf bank_mask:0xf bound_ctrl:1
	v_fmac_f32_dpp v7, v27, v224 row_newbcast:10 row_mask:0xf bank_mask:0xf bound_ctrl:1
	v_fmac_f32_dpp v6, v27, v224 row_newbcast:11 row_mask:0xf bank_mask:0xf bound_ctrl:1
	v_fmac_f32_dpp v5, v27, v224 row_newbcast:12 row_mask:0xf bank_mask:0xf bound_ctrl:1
	v_fmac_f32_dpp v4, v27, v224 row_newbcast:13 row_mask:0xf bank_mask:0xf bound_ctrl:1
	v_fmac_f32_dpp v3, v27, v224 row_newbcast:14 row_mask:0xf bank_mask:0xf bound_ctrl:1
	v_fmac_f32_dpp v2, v27, v224 row_newbcast:15 row_mask:0xf bank_mask:0xf bound_ctrl:1
	s_nop 0
	v_add_f32 v37, v37, v40
	s_nop 0
	s_nop 0
	v_mfma_f32_16x16x4_f32 v[232:235], v228, v37, 0
	ds_write_b64 v22, v[24:25] offset:63488
	v_fmac_f32_dpp v17, v28, v34 row_newbcast:0 row_mask:0xf bank_mask:0xf bound_ctrl:1
	v_fmac_f32_dpp v16, v28, v34 row_newbcast:1 row_mask:0xf bank_mask:0xf bound_ctrl:1
	v_fmac_f32_dpp v15, v28, v34 row_newbcast:2 row_mask:0xf bank_mask:0xf bound_ctrl:1
	v_fmac_f32_dpp v14, v28, v34 row_newbcast:3 row_mask:0xf bank_mask:0xf bound_ctrl:1
	v_fmac_f32_dpp v13, v28, v34 row_newbcast:4 row_mask:0xf bank_mask:0xf bound_ctrl:1
	v_fmac_f32_dpp v12, v28, v34 row_newbcast:5 row_mask:0xf bank_mask:0xf bound_ctrl:1
	v_fmac_f32_dpp v11, v28, v34 row_newbcast:6 row_mask:0xf bank_mask:0xf bound_ctrl:1
	v_fmac_f32_dpp v10, v28, v34 row_newbcast:7 row_mask:0xf bank_mask:0xf bound_ctrl:1
	v_fmac_f32_dpp v9, v28, v34 row_newbcast:8 row_mask:0xf bank_mask:0xf bound_ctrl:1
	v_fmac_f32_dpp v8, v28, v34 row_newbcast:9 row_mask:0xf bank_mask:0xf bound_ctrl:1
	v_fmac_f32_dpp v7, v28, v34 row_newbcast:10 row_mask:0xf bank_mask:0xf bound_ctrl:1
	v_fmac_f32_dpp v6, v28, v34 row_newbcast:11 row_mask:0xf bank_mask:0xf bound_ctrl:1
	v_fmac_f32_dpp v5, v28, v34 row_newbcast:12 row_mask:0xf bank_mask:0xf bound_ctrl:1
	v_fmac_f32_dpp v4, v28, v34 row_newbcast:13 row_mask:0xf bank_mask:0xf bound_ctrl:1
	v_fmac_f32_dpp v3, v28, v34 row_newbcast:14 row_mask:0xf bank_mask:0xf bound_ctrl:1
	v_fmac_f32_dpp v2, v28, v34 row_newbcast:15 row_mask:0xf bank_mask:0xf bound_ctrl:1
	v_mul_f32_dpp v22, v29, v17 row_newbcast:0 row_mask:0xf bank_mask:0xf bound_ctrl:1
	v_mul_f32_dpp v23, v29, v16 row_newbcast:1 row_mask:0xf bank_mask:0xf bound_ctrl:1
	v_fmac_f32_dpp v22, v29, v15 row_newbcast:2 row_mask:0xf bank_mask:0xf bound_ctrl:1
	v_fmac_f32_dpp v23, v29, v14 row_newbcast:3 row_mask:0xf bank_mask:0xf bound_ctrl:1
	v_fmac_f32_dpp v22, v29, v13 row_newbcast:4 row_mask:0xf bank_mask:0xf bound_ctrl:1
	v_fmac_f32_dpp v23, v29, v12 row_newbcast:5 row_mask:0xf bank_mask:0xf bound_ctrl:1
	v_fmac_f32_dpp v22, v29, v11 row_newbcast:6 row_mask:0xf bank_mask:0xf bound_ctrl:1
	v_fmac_f32_dpp v23, v29, v10 row_newbcast:7 row_mask:0xf bank_mask:0xf bound_ctrl:1
	s_nop 0
	v_fmac_f32_dpp v22, v29, v9 row_newbcast:8 row_mask:0xf bank_mask:0xf bound_ctrl:1
	v_fmac_f32_dpp v23, v29, v8 row_newbcast:9 row_mask:0xf bank_mask:0xf bound_ctrl:1
	v_fmac_f32_dpp v22, v29, v7 row_newbcast:10 row_mask:0xf bank_mask:0xf bound_ctrl:1
	v_fmac_f32_dpp v23, v29, v6 row_newbcast:11 row_mask:0xf bank_mask:0xf bound_ctrl:1
	s_nop 0
	v_fmac_f32_dpp v22, v29, v5 row_newbcast:12 row_mask:0xf bank_mask:0xf bound_ctrl:1
	v_fmac_f32_dpp v23, v29, v4 row_newbcast:13 row_mask:0xf bank_mask:0xf bound_ctrl:1
	v_fmac_f32_dpp v22, v29, v3 row_newbcast:14 row_mask:0xf bank_mask:0xf bound_ctrl:1
	v_fmac_f32_dpp v23, v29, v2 row_newbcast:15 row_mask:0xf bank_mask:0xf bound_ctrl:1
	s_waitcnt lgkmcnt(0)
	ds_read_b32 v38, v19 offset:23040
	ds_read2st64_b32 v[24:25], v21 offset0:26 offset1:42
	ds_read2st64_b32 v[26:27], v21 offset0:58 offset1:74
	v_mul_f32_dpp v39, v30, v17 row_newbcast:0 row_mask:0xf bank_mask:0xf bound_ctrl:1
	v_mul_f32_dpp v29, v30, v16 row_newbcast:1 row_mask:0xf bank_mask:0xf bound_ctrl:1
	v_fmac_f32_dpp v39, v30, v15 row_newbcast:2 row_mask:0xf bank_mask:0xf bound_ctrl:1
	v_fmac_f32_dpp v29, v30, v14 row_newbcast:3 row_mask:0xf bank_mask:0xf bound_ctrl:1
	v_fmac_f32_dpp v232, v229, v224 row_newbcast:8 row_mask:0xf bank_mask:0xf bound_ctrl:1
	v_fmac_f32_dpp v39, v30, v13 row_newbcast:4 row_mask:0xf bank_mask:0xf bound_ctrl:1
	v_fmac_f32_dpp v29, v30, v12 row_newbcast:5 row_mask:0xf bank_mask:0xf bound_ctrl:1
	v_fmac_f32_dpp v39, v30, v11 row_newbcast:6 row_mask:0xf bank_mask:0xf bound_ctrl:1
	v_fmac_f32_dpp v29, v30, v10 row_newbcast:7 row_mask:0xf bank_mask:0xf bound_ctrl:1
	v_fmac_f32_dpp v232, v230, v34 row_newbcast:8 row_mask:0xf bank_mask:0xf bound_ctrl:1
	v_fmac_f32_dpp v39, v30, v9 row_newbcast:8 row_mask:0xf bank_mask:0xf bound_ctrl:1
	v_fmac_f32_dpp v29, v30, v8 row_newbcast:9 row_mask:0xf bank_mask:0xf bound_ctrl:1
	v_fmac_f32_dpp v39, v30, v7 row_newbcast:10 row_mask:0xf bank_mask:0xf bound_ctrl:1
	v_fmac_f32_dpp v29, v30, v6 row_newbcast:11 row_mask:0xf bank_mask:0xf bound_ctrl:1
	s_nop 0
	v_fmac_f32_dpp v39, v30, v5 row_newbcast:12 row_mask:0xf bank_mask:0xf bound_ctrl:1
	v_fmac_f32_dpp v29, v30, v4 row_newbcast:13 row_mask:0xf bank_mask:0xf bound_ctrl:1
	v_fmac_f32_dpp v39, v30, v3 row_newbcast:14 row_mask:0xf bank_mask:0xf bound_ctrl:1
	v_fmac_f32_dpp v29, v30, v2 row_newbcast:15 row_mask:0xf bank_mask:0xf bound_ctrl:1
	v_fmac_f32_dpp v17, v31, v232 row_newbcast:0 row_mask:0xf bank_mask:0xf bound_ctrl:1
	v_fmac_f32_dpp v16, v31, v232 row_newbcast:1 row_mask:0xf bank_mask:0xf bound_ctrl:1
	v_fmac_f32_dpp v15, v31, v232 row_newbcast:2 row_mask:0xf bank_mask:0xf bound_ctrl:1
	v_fmac_f32_dpp v14, v31, v232 row_newbcast:3 row_mask:0xf bank_mask:0xf bound_ctrl:1
	v_fmac_f32_dpp v13, v31, v232 row_newbcast:4 row_mask:0xf bank_mask:0xf bound_ctrl:1
	v_fmac_f32_dpp v12, v31, v232 row_newbcast:5 row_mask:0xf bank_mask:0xf bound_ctrl:1
	v_fmac_f32_dpp v11, v31, v232 row_newbcast:6 row_mask:0xf bank_mask:0xf bound_ctrl:1
	v_fmac_f32_dpp v10, v31, v232 row_newbcast:7 row_mask:0xf bank_mask:0xf bound_ctrl:1
	v_fmac_f32_dpp v9, v31, v232 row_newbcast:8 row_mask:0xf bank_mask:0xf bound_ctrl:1
	v_fmac_f32_dpp v8, v31, v232 row_newbcast:9 row_mask:0xf bank_mask:0xf bound_ctrl:1
	v_fmac_f32_dpp v7, v31, v232 row_newbcast:10 row_mask:0xf bank_mask:0xf bound_ctrl:1
	v_fmac_f32_dpp v6, v31, v232 row_newbcast:11 row_mask:0xf bank_mask:0xf bound_ctrl:1
	v_fmac_f32_dpp v5, v31, v232 row_newbcast:12 row_mask:0xf bank_mask:0xf bound_ctrl:1
	v_fmac_f32_dpp v4, v31, v232 row_newbcast:13 row_mask:0xf bank_mask:0xf bound_ctrl:1
	v_fmac_f32_dpp v3, v31, v232 row_newbcast:14 row_mask:0xf bank_mask:0xf bound_ctrl:1
	v_fmac_f32_dpp v2, v31, v232 row_newbcast:15 row_mask:0xf bank_mask:0xf bound_ctrl:1
	s_nop 0
	v_add_f32 v39, v39, v29
	s_nop 0
	s_nop 0
	v_mfma_f32_16x16x4_f32 v[224:227], v228, v39, 0
	ds_write_b64 v20, v[22:23] offset:16384
	v_fmac_f32_dpp v17, v32, v36 row_newbcast:0 row_mask:0xf bank_mask:0xf bound_ctrl:1
	v_fmac_f32_dpp v16, v32, v36 row_newbcast:1 row_mask:0xf bank_mask:0xf bound_ctrl:1
	v_fmac_f32_dpp v15, v32, v36 row_newbcast:2 row_mask:0xf bank_mask:0xf bound_ctrl:1
	v_fmac_f32_dpp v14, v32, v36 row_newbcast:3 row_mask:0xf bank_mask:0xf bound_ctrl:1
	v_fmac_f32_dpp v13, v32, v36 row_newbcast:4 row_mask:0xf bank_mask:0xf bound_ctrl:1
	v_fmac_f32_dpp v12, v32, v36 row_newbcast:5 row_mask:0xf bank_mask:0xf bound_ctrl:1
	v_fmac_f32_dpp v11, v32, v36 row_newbcast:6 row_mask:0xf bank_mask:0xf bound_ctrl:1
	v_fmac_f32_dpp v10, v32, v36 row_newbcast:7 row_mask:0xf bank_mask:0xf bound_ctrl:1
	v_fmac_f32_dpp v9, v32, v36 row_newbcast:8 row_mask:0xf bank_mask:0xf bound_ctrl:1
	v_fmac_f32_dpp v8, v32, v36 row_newbcast:9 row_mask:0xf bank_mask:0xf bound_ctrl:1
	v_fmac_f32_dpp v7, v32, v36 row_newbcast:10 row_mask:0xf bank_mask:0xf bound_ctrl:1
	v_fmac_f32_dpp v6, v32, v36 row_newbcast:11 row_mask:0xf bank_mask:0xf bound_ctrl:1
	v_fmac_f32_dpp v5, v32, v36 row_newbcast:12 row_mask:0xf bank_mask:0xf bound_ctrl:1
	v_fmac_f32_dpp v4, v32, v36 row_newbcast:13 row_mask:0xf bank_mask:0xf bound_ctrl:1
	v_fmac_f32_dpp v3, v32, v36 row_newbcast:14 row_mask:0xf bank_mask:0xf bound_ctrl:1
	v_fmac_f32_dpp v2, v32, v36 row_newbcast:15 row_mask:0xf bank_mask:0xf bound_ctrl:1
	v_mul_f32_dpp v22, v33, v17 row_newbcast:0 row_mask:0xf bank_mask:0xf bound_ctrl:1
	v_mul_f32_dpp v23, v33, v16 row_newbcast:1 row_mask:0xf bank_mask:0xf bound_ctrl:1
	v_fmac_f32_dpp v22, v33, v15 row_newbcast:2 row_mask:0xf bank_mask:0xf bound_ctrl:1
	v_fmac_f32_dpp v23, v33, v14 row_newbcast:3 row_mask:0xf bank_mask:0xf bound_ctrl:1
	v_fmac_f32_dpp v22, v33, v13 row_newbcast:4 row_mask:0xf bank_mask:0xf bound_ctrl:1
	v_fmac_f32_dpp v23, v33, v12 row_newbcast:5 row_mask:0xf bank_mask:0xf bound_ctrl:1
	v_fmac_f32_dpp v22, v33, v11 row_newbcast:6 row_mask:0xf bank_mask:0xf bound_ctrl:1
	v_fmac_f32_dpp v23, v33, v10 row_newbcast:7 row_mask:0xf bank_mask:0xf bound_ctrl:1
	s_nop 0
	v_fmac_f32_dpp v22, v33, v9 row_newbcast:8 row_mask:0xf bank_mask:0xf bound_ctrl:1
	v_fmac_f32_dpp v23, v33, v8 row_newbcast:9 row_mask:0xf bank_mask:0xf bound_ctrl:1
	v_fmac_f32_dpp v22, v33, v7 row_newbcast:10 row_mask:0xf bank_mask:0xf bound_ctrl:1
	v_fmac_f32_dpp v23, v33, v6 row_newbcast:11 row_mask:0xf bank_mask:0xf bound_ctrl:1
	s_nop 0
	v_fmac_f32_dpp v22, v33, v5 row_newbcast:12 row_mask:0xf bank_mask:0xf bound_ctrl:1
	v_fmac_f32_dpp v23, v33, v4 row_newbcast:13 row_mask:0xf bank_mask:0xf bound_ctrl:1
	v_fmac_f32_dpp v22, v33, v3 row_newbcast:14 row_mask:0xf bank_mask:0xf bound_ctrl:1
	v_fmac_f32_dpp v23, v33, v2 row_newbcast:15 row_mask:0xf bank_mask:0xf bound_ctrl:1
	s_waitcnt lgkmcnt(0)
	ds_read_b32 v33, v19 offset:23296
	ds_read2st64_b32 v[28:29], v21 offset0:27 offset1:43
	ds_read2st64_b32 v[30:31], v21 offset0:59 offset1:75
	v_mul_f32_dpp v34, v24, v17 row_newbcast:0 row_mask:0xf bank_mask:0xf bound_ctrl:1
	v_mul_f32_dpp v35, v24, v16 row_newbcast:1 row_mask:0xf bank_mask:0xf bound_ctrl:1
	v_fmac_f32_dpp v34, v24, v15 row_newbcast:2 row_mask:0xf bank_mask:0xf bound_ctrl:1
	v_fmac_f32_dpp v35, v24, v14 row_newbcast:3 row_mask:0xf bank_mask:0xf bound_ctrl:1
	v_fmac_f32_dpp v224, v229, v232 row_newbcast:9 row_mask:0xf bank_mask:0xf bound_ctrl:1
	v_fmac_f32_dpp v34, v24, v13 row_newbcast:4 row_mask:0xf bank_mask:0xf bound_ctrl:1
	v_fmac_f32_dpp v35, v24, v12 row_newbcast:5 row_mask:0xf bank_mask:0xf bound_ctrl:1
	v_fmac_f32_dpp v34, v24, v11 row_newbcast:6 row_mask:0xf bank_mask:0xf bound_ctrl:1
	v_fmac_f32_dpp v35, v24, v10 row_newbcast:7 row_mask:0xf bank_mask:0xf bound_ctrl:1
	v_fmac_f32_dpp v224, v230, v36 row_newbcast:9 row_mask:0xf bank_mask:0xf bound_ctrl:1
	v_fmac_f32_dpp v34, v24, v9 row_newbcast:8 row_mask:0xf bank_mask:0xf bound_ctrl:1
	v_fmac_f32_dpp v35, v24, v8 row_newbcast:9 row_mask:0xf bank_mask:0xf bound_ctrl:1
	v_fmac_f32_dpp v34, v24, v7 row_newbcast:10 row_mask:0xf bank_mask:0xf bound_ctrl:1
	v_fmac_f32_dpp v35, v24, v6 row_newbcast:11 row_mask:0xf bank_mask:0xf bound_ctrl:1
	s_nop 0
	v_fmac_f32_dpp v34, v24, v5 row_newbcast:12 row_mask:0xf bank_mask:0xf bound_ctrl:1
	v_fmac_f32_dpp v35, v24, v4 row_newbcast:13 row_mask:0xf bank_mask:0xf bound_ctrl:1
	v_fmac_f32_dpp v34, v24, v3 row_newbcast:14 row_mask:0xf bank_mask:0xf bound_ctrl:1
	v_fmac_f32_dpp v35, v24, v2 row_newbcast:15 row_mask:0xf bank_mask:0xf bound_ctrl:1
	v_fmac_f32_dpp v17, v25, v224 row_newbcast:0 row_mask:0xf bank_mask:0xf bound_ctrl:1
	v_fmac_f32_dpp v16, v25, v224 row_newbcast:1 row_mask:0xf bank_mask:0xf bound_ctrl:1
	v_fmac_f32_dpp v15, v25, v224 row_newbcast:2 row_mask:0xf bank_mask:0xf bound_ctrl:1
	v_fmac_f32_dpp v14, v25, v224 row_newbcast:3 row_mask:0xf bank_mask:0xf bound_ctrl:1
	v_fmac_f32_dpp v13, v25, v224 row_newbcast:4 row_mask:0xf bank_mask:0xf bound_ctrl:1
	v_fmac_f32_dpp v12, v25, v224 row_newbcast:5 row_mask:0xf bank_mask:0xf bound_ctrl:1
	v_fmac_f32_dpp v11, v25, v224 row_newbcast:6 row_mask:0xf bank_mask:0xf bound_ctrl:1
	v_fmac_f32_dpp v10, v25, v224 row_newbcast:7 row_mask:0xf bank_mask:0xf bound_ctrl:1
	v_fmac_f32_dpp v9, v25, v224 row_newbcast:8 row_mask:0xf bank_mask:0xf bound_ctrl:1
	v_fmac_f32_dpp v8, v25, v224 row_newbcast:9 row_mask:0xf bank_mask:0xf bound_ctrl:1
	v_fmac_f32_dpp v7, v25, v224 row_newbcast:10 row_mask:0xf bank_mask:0xf bound_ctrl:1
	v_fmac_f32_dpp v6, v25, v224 row_newbcast:11 row_mask:0xf bank_mask:0xf bound_ctrl:1
	v_fmac_f32_dpp v5, v25, v224 row_newbcast:12 row_mask:0xf bank_mask:0xf bound_ctrl:1
	v_fmac_f32_dpp v4, v25, v224 row_newbcast:13 row_mask:0xf bank_mask:0xf bound_ctrl:1
	v_fmac_f32_dpp v3, v25, v224 row_newbcast:14 row_mask:0xf bank_mask:0xf bound_ctrl:1
	v_fmac_f32_dpp v2, v25, v224 row_newbcast:15 row_mask:0xf bank_mask:0xf bound_ctrl:1
	s_nop 0
	v_add_f32 v34, v34, v35
	s_nop 0
	s_nop 0
	v_mfma_f32_16x16x4_f32 v[232:235], v228, v34, 0
	ds_write_b64 v20, v[22:23] offset:18432
	v_fmac_f32_dpp v17, v26, v38 row_newbcast:0 row_mask:0xf bank_mask:0xf bound_ctrl:1
	v_fmac_f32_dpp v16, v26, v38 row_newbcast:1 row_mask:0xf bank_mask:0xf bound_ctrl:1
	v_fmac_f32_dpp v15, v26, v38 row_newbcast:2 row_mask:0xf bank_mask:0xf bound_ctrl:1
	v_fmac_f32_dpp v14, v26, v38 row_newbcast:3 row_mask:0xf bank_mask:0xf bound_ctrl:1
	v_fmac_f32_dpp v13, v26, v38 row_newbcast:4 row_mask:0xf bank_mask:0xf bound_ctrl:1
	v_fmac_f32_dpp v12, v26, v38 row_newbcast:5 row_mask:0xf bank_mask:0xf bound_ctrl:1
	v_fmac_f32_dpp v11, v26, v38 row_newbcast:6 row_mask:0xf bank_mask:0xf bound_ctrl:1
	v_fmac_f32_dpp v10, v26, v38 row_newbcast:7 row_mask:0xf bank_mask:0xf bound_ctrl:1
	v_fmac_f32_dpp v9, v26, v38 row_newbcast:8 row_mask:0xf bank_mask:0xf bound_ctrl:1
	v_fmac_f32_dpp v8, v26, v38 row_newbcast:9 row_mask:0xf bank_mask:0xf bound_ctrl:1
	v_fmac_f32_dpp v7, v26, v38 row_newbcast:10 row_mask:0xf bank_mask:0xf bound_ctrl:1
	v_fmac_f32_dpp v6, v26, v38 row_newbcast:11 row_mask:0xf bank_mask:0xf bound_ctrl:1
	v_fmac_f32_dpp v5, v26, v38 row_newbcast:12 row_mask:0xf bank_mask:0xf bound_ctrl:1
	v_fmac_f32_dpp v4, v26, v38 row_newbcast:13 row_mask:0xf bank_mask:0xf bound_ctrl:1
	v_fmac_f32_dpp v3, v26, v38 row_newbcast:14 row_mask:0xf bank_mask:0xf bound_ctrl:1
	v_fmac_f32_dpp v2, v26, v38 row_newbcast:15 row_mask:0xf bank_mask:0xf bound_ctrl:1
	v_mul_f32_dpp v22, v27, v17 row_newbcast:0 row_mask:0xf bank_mask:0xf bound_ctrl:1
	v_mul_f32_dpp v23, v27, v16 row_newbcast:1 row_mask:0xf bank_mask:0xf bound_ctrl:1
	v_fmac_f32_dpp v22, v27, v15 row_newbcast:2 row_mask:0xf bank_mask:0xf bound_ctrl:1
	v_fmac_f32_dpp v23, v27, v14 row_newbcast:3 row_mask:0xf bank_mask:0xf bound_ctrl:1
	v_fmac_f32_dpp v22, v27, v13 row_newbcast:4 row_mask:0xf bank_mask:0xf bound_ctrl:1
	v_fmac_f32_dpp v23, v27, v12 row_newbcast:5 row_mask:0xf bank_mask:0xf bound_ctrl:1
	v_fmac_f32_dpp v22, v27, v11 row_newbcast:6 row_mask:0xf bank_mask:0xf bound_ctrl:1
	v_fmac_f32_dpp v23, v27, v10 row_newbcast:7 row_mask:0xf bank_mask:0xf bound_ctrl:1
	s_nop 0
	v_fmac_f32_dpp v22, v27, v9 row_newbcast:8 row_mask:0xf bank_mask:0xf bound_ctrl:1
	v_fmac_f32_dpp v23, v27, v8 row_newbcast:9 row_mask:0xf bank_mask:0xf bound_ctrl:1
	v_fmac_f32_dpp v22, v27, v7 row_newbcast:10 row_mask:0xf bank_mask:0xf bound_ctrl:1
	v_fmac_f32_dpp v23, v27, v6 row_newbcast:11 row_mask:0xf bank_mask:0xf bound_ctrl:1
	s_nop 0
	v_fmac_f32_dpp v22, v27, v5 row_newbcast:12 row_mask:0xf bank_mask:0xf bound_ctrl:1
	v_fmac_f32_dpp v23, v27, v4 row_newbcast:13 row_mask:0xf bank_mask:0xf bound_ctrl:1
	v_fmac_f32_dpp v22, v27, v3 row_newbcast:14 row_mask:0xf bank_mask:0xf bound_ctrl:1
	v_fmac_f32_dpp v23, v27, v2 row_newbcast:15 row_mask:0xf bank_mask:0xf bound_ctrl:1
	s_waitcnt lgkmcnt(0)
	ds_read_b32 v35, v19 offset:23552
	ds_read2st64_b32 v[24:25], v21 offset0:28 offset1:44
	ds_read2st64_b32 v[26:27], v21 offset0:60 offset1:76
	v_mul_f32_dpp v36, v28, v17 row_newbcast:0 row_mask:0xf bank_mask:0xf bound_ctrl:1
	v_mul_f32_dpp v37, v28, v16 row_newbcast:1 row_mask:0xf bank_mask:0xf bound_ctrl:1
	v_fmac_f32_dpp v36, v28, v15 row_newbcast:2 row_mask:0xf bank_mask:0xf bound_ctrl:1
	v_fmac_f32_dpp v37, v28, v14 row_newbcast:3 row_mask:0xf bank_mask:0xf bound_ctrl:1
	v_fmac_f32_dpp v232, v229, v224 row_newbcast:10 row_mask:0xf bank_mask:0xf bound_ctrl:1
	v_fmac_f32_dpp v36, v28, v13 row_newbcast:4 row_mask:0xf bank_mask:0xf bound_ctrl:1
	v_fmac_f32_dpp v37, v28, v12 row_newbcast:5 row_mask:0xf bank_mask:0xf bound_ctrl:1
	v_fmac_f32_dpp v36, v28, v11 row_newbcast:6 row_mask:0xf bank_mask:0xf bound_ctrl:1
	v_fmac_f32_dpp v37, v28, v10 row_newbcast:7 row_mask:0xf bank_mask:0xf bound_ctrl:1
	v_fmac_f32_dpp v232, v230, v38 row_newbcast:10 row_mask:0xf bank_mask:0xf bound_ctrl:1
	v_fmac_f32_dpp v36, v28, v9 row_newbcast:8 row_mask:0xf bank_mask:0xf bound_ctrl:1
	v_fmac_f32_dpp v37, v28, v8 row_newbcast:9 row_mask:0xf bank_mask:0xf bound_ctrl:1
	v_fmac_f32_dpp v36, v28, v7 row_newbcast:10 row_mask:0xf bank_mask:0xf bound_ctrl:1
	v_fmac_f32_dpp v37, v28, v6 row_newbcast:11 row_mask:0xf bank_mask:0xf bound_ctrl:1
	s_nop 0
	v_fmac_f32_dpp v36, v28, v5 row_newbcast:12 row_mask:0xf bank_mask:0xf bound_ctrl:1
	v_fmac_f32_dpp v37, v28, v4 row_newbcast:13 row_mask:0xf bank_mask:0xf bound_ctrl:1
	v_fmac_f32_dpp v36, v28, v3 row_newbcast:14 row_mask:0xf bank_mask:0xf bound_ctrl:1
	v_fmac_f32_dpp v37, v28, v2 row_newbcast:15 row_mask:0xf bank_mask:0xf bound_ctrl:1
	v_fmac_f32_dpp v17, v29, v232 row_newbcast:0 row_mask:0xf bank_mask:0xf bound_ctrl:1
	v_fmac_f32_dpp v16, v29, v232 row_newbcast:1 row_mask:0xf bank_mask:0xf bound_ctrl:1
	v_fmac_f32_dpp v15, v29, v232 row_newbcast:2 row_mask:0xf bank_mask:0xf bound_ctrl:1
	v_fmac_f32_dpp v14, v29, v232 row_newbcast:3 row_mask:0xf bank_mask:0xf bound_ctrl:1
	v_fmac_f32_dpp v13, v29, v232 row_newbcast:4 row_mask:0xf bank_mask:0xf bound_ctrl:1
	v_fmac_f32_dpp v12, v29, v232 row_newbcast:5 row_mask:0xf bank_mask:0xf bound_ctrl:1
	v_fmac_f32_dpp v11, v29, v232 row_newbcast:6 row_mask:0xf bank_mask:0xf bound_ctrl:1
	v_fmac_f32_dpp v10, v29, v232 row_newbcast:7 row_mask:0xf bank_mask:0xf bound_ctrl:1
	v_fmac_f32_dpp v9, v29, v232 row_newbcast:8 row_mask:0xf bank_mask:0xf bound_ctrl:1
	v_fmac_f32_dpp v8, v29, v232 row_newbcast:9 row_mask:0xf bank_mask:0xf bound_ctrl:1
	v_fmac_f32_dpp v7, v29, v232 row_newbcast:10 row_mask:0xf bank_mask:0xf bound_ctrl:1
	v_fmac_f32_dpp v6, v29, v232 row_newbcast:11 row_mask:0xf bank_mask:0xf bound_ctrl:1
	v_fmac_f32_dpp v5, v29, v232 row_newbcast:12 row_mask:0xf bank_mask:0xf bound_ctrl:1
	v_fmac_f32_dpp v4, v29, v232 row_newbcast:13 row_mask:0xf bank_mask:0xf bound_ctrl:1
	v_fmac_f32_dpp v3, v29, v232 row_newbcast:14 row_mask:0xf bank_mask:0xf bound_ctrl:1
	v_fmac_f32_dpp v2, v29, v232 row_newbcast:15 row_mask:0xf bank_mask:0xf bound_ctrl:1
	s_nop 0
	v_add_f32 v36, v36, v37
	s_nop 0
	s_nop 0
	v_mfma_f32_16x16x4_f32 v[224:227], v228, v36, 0
	ds_write_b64 v20, v[22:23] offset:20480
	v_fmac_f32_dpp v17, v30, v33 row_newbcast:0 row_mask:0xf bank_mask:0xf bound_ctrl:1
	v_fmac_f32_dpp v16, v30, v33 row_newbcast:1 row_mask:0xf bank_mask:0xf bound_ctrl:1
	v_fmac_f32_dpp v15, v30, v33 row_newbcast:2 row_mask:0xf bank_mask:0xf bound_ctrl:1
	v_fmac_f32_dpp v14, v30, v33 row_newbcast:3 row_mask:0xf bank_mask:0xf bound_ctrl:1
	v_fmac_f32_dpp v13, v30, v33 row_newbcast:4 row_mask:0xf bank_mask:0xf bound_ctrl:1
	v_fmac_f32_dpp v12, v30, v33 row_newbcast:5 row_mask:0xf bank_mask:0xf bound_ctrl:1
	v_fmac_f32_dpp v11, v30, v33 row_newbcast:6 row_mask:0xf bank_mask:0xf bound_ctrl:1
	v_fmac_f32_dpp v10, v30, v33 row_newbcast:7 row_mask:0xf bank_mask:0xf bound_ctrl:1
	v_fmac_f32_dpp v9, v30, v33 row_newbcast:8 row_mask:0xf bank_mask:0xf bound_ctrl:1
	v_fmac_f32_dpp v8, v30, v33 row_newbcast:9 row_mask:0xf bank_mask:0xf bound_ctrl:1
	v_fmac_f32_dpp v7, v30, v33 row_newbcast:10 row_mask:0xf bank_mask:0xf bound_ctrl:1
	v_fmac_f32_dpp v6, v30, v33 row_newbcast:11 row_mask:0xf bank_mask:0xf bound_ctrl:1
	v_fmac_f32_dpp v5, v30, v33 row_newbcast:12 row_mask:0xf bank_mask:0xf bound_ctrl:1
	v_fmac_f32_dpp v4, v30, v33 row_newbcast:13 row_mask:0xf bank_mask:0xf bound_ctrl:1
	v_fmac_f32_dpp v3, v30, v33 row_newbcast:14 row_mask:0xf bank_mask:0xf bound_ctrl:1
	v_fmac_f32_dpp v2, v30, v33 row_newbcast:15 row_mask:0xf bank_mask:0xf bound_ctrl:1
	v_mul_f32_dpp v22, v31, v17 row_newbcast:0 row_mask:0xf bank_mask:0xf bound_ctrl:1
	v_mul_f32_dpp v23, v31, v16 row_newbcast:1 row_mask:0xf bank_mask:0xf bound_ctrl:1
	v_fmac_f32_dpp v22, v31, v15 row_newbcast:2 row_mask:0xf bank_mask:0xf bound_ctrl:1
	v_fmac_f32_dpp v23, v31, v14 row_newbcast:3 row_mask:0xf bank_mask:0xf bound_ctrl:1
	v_fmac_f32_dpp v22, v31, v13 row_newbcast:4 row_mask:0xf bank_mask:0xf bound_ctrl:1
	v_fmac_f32_dpp v23, v31, v12 row_newbcast:5 row_mask:0xf bank_mask:0xf bound_ctrl:1
	v_fmac_f32_dpp v22, v31, v11 row_newbcast:6 row_mask:0xf bank_mask:0xf bound_ctrl:1
	v_fmac_f32_dpp v23, v31, v10 row_newbcast:7 row_mask:0xf bank_mask:0xf bound_ctrl:1
	s_nop 0
	v_fmac_f32_dpp v22, v31, v9 row_newbcast:8 row_mask:0xf bank_mask:0xf bound_ctrl:1
	v_fmac_f32_dpp v23, v31, v8 row_newbcast:9 row_mask:0xf bank_mask:0xf bound_ctrl:1
	v_fmac_f32_dpp v22, v31, v7 row_newbcast:10 row_mask:0xf bank_mask:0xf bound_ctrl:1
	v_fmac_f32_dpp v23, v31, v6 row_newbcast:11 row_mask:0xf bank_mask:0xf bound_ctrl:1
	s_nop 0
	v_fmac_f32_dpp v22, v31, v5 row_newbcast:12 row_mask:0xf bank_mask:0xf bound_ctrl:1
	v_fmac_f32_dpp v23, v31, v4 row_newbcast:13 row_mask:0xf bank_mask:0xf bound_ctrl:1
	v_fmac_f32_dpp v22, v31, v3 row_newbcast:14 row_mask:0xf bank_mask:0xf bound_ctrl:1
	v_fmac_f32_dpp v23, v31, v2 row_newbcast:15 row_mask:0xf bank_mask:0xf bound_ctrl:1
	s_waitcnt lgkmcnt(0)
	ds_read_b32 v37, v19 offset:23808
	ds_read2st64_b32 v[28:29], v21 offset0:29 offset1:45
	ds_read2st64_b32 v[30:31], v21 offset0:61 offset1:77
	v_mul_f32_dpp v38, v24, v17 row_newbcast:0 row_mask:0xf bank_mask:0xf bound_ctrl:1
	v_mul_f32_dpp v39, v24, v16 row_newbcast:1 row_mask:0xf bank_mask:0xf bound_ctrl:1
	v_fmac_f32_dpp v38, v24, v15 row_newbcast:2 row_mask:0xf bank_mask:0xf bound_ctrl:1
	v_fmac_f32_dpp v39, v24, v14 row_newbcast:3 row_mask:0xf bank_mask:0xf bound_ctrl:1
	v_fmac_f32_dpp v224, v229, v232 row_newbcast:11 row_mask:0xf bank_mask:0xf bound_ctrl:1
	v_fmac_f32_dpp v38, v24, v13 row_newbcast:4 row_mask:0xf bank_mask:0xf bound_ctrl:1
	v_fmac_f32_dpp v39, v24, v12 row_newbcast:5 row_mask:0xf bank_mask:0xf bound_ctrl:1
	v_fmac_f32_dpp v38, v24, v11 row_newbcast:6 row_mask:0xf bank_mask:0xf bound_ctrl:1
	v_fmac_f32_dpp v39, v24, v10 row_newbcast:7 row_mask:0xf bank_mask:0xf bound_ctrl:1
	v_fmac_f32_dpp v224, v230, v33 row_newbcast:11 row_mask:0xf bank_mask:0xf bound_ctrl:1
	v_fmac_f32_dpp v38, v24, v9 row_newbcast:8 row_mask:0xf bank_mask:0xf bound_ctrl:1
	v_fmac_f32_dpp v39, v24, v8 row_newbcast:9 row_mask:0xf bank_mask:0xf bound_ctrl:1
	v_fmac_f32_dpp v38, v24, v7 row_newbcast:10 row_mask:0xf bank_mask:0xf bound_ctrl:1
	v_fmac_f32_dpp v39, v24, v6 row_newbcast:11 row_mask:0xf bank_mask:0xf bound_ctrl:1
	s_nop 0
	v_fmac_f32_dpp v38, v24, v5 row_newbcast:12 row_mask:0xf bank_mask:0xf bound_ctrl:1
	v_fmac_f32_dpp v39, v24, v4 row_newbcast:13 row_mask:0xf bank_mask:0xf bound_ctrl:1
	v_fmac_f32_dpp v38, v24, v3 row_newbcast:14 row_mask:0xf bank_mask:0xf bound_ctrl:1
	v_fmac_f32_dpp v39, v24, v2 row_newbcast:15 row_mask:0xf bank_mask:0xf bound_ctrl:1
	v_fmac_f32_dpp v17, v25, v224 row_newbcast:0 row_mask:0xf bank_mask:0xf bound_ctrl:1
	v_fmac_f32_dpp v16, v25, v224 row_newbcast:1 row_mask:0xf bank_mask:0xf bound_ctrl:1
	v_fmac_f32_dpp v15, v25, v224 row_newbcast:2 row_mask:0xf bank_mask:0xf bound_ctrl:1
	v_fmac_f32_dpp v14, v25, v224 row_newbcast:3 row_mask:0xf bank_mask:0xf bound_ctrl:1
	v_fmac_f32_dpp v13, v25, v224 row_newbcast:4 row_mask:0xf bank_mask:0xf bound_ctrl:1
	v_fmac_f32_dpp v12, v25, v224 row_newbcast:5 row_mask:0xf bank_mask:0xf bound_ctrl:1
	v_fmac_f32_dpp v11, v25, v224 row_newbcast:6 row_mask:0xf bank_mask:0xf bound_ctrl:1
	v_fmac_f32_dpp v10, v25, v224 row_newbcast:7 row_mask:0xf bank_mask:0xf bound_ctrl:1
	v_fmac_f32_dpp v9, v25, v224 row_newbcast:8 row_mask:0xf bank_mask:0xf bound_ctrl:1
	v_fmac_f32_dpp v8, v25, v224 row_newbcast:9 row_mask:0xf bank_mask:0xf bound_ctrl:1
	v_fmac_f32_dpp v7, v25, v224 row_newbcast:10 row_mask:0xf bank_mask:0xf bound_ctrl:1
	v_fmac_f32_dpp v6, v25, v224 row_newbcast:11 row_mask:0xf bank_mask:0xf bound_ctrl:1
	v_fmac_f32_dpp v5, v25, v224 row_newbcast:12 row_mask:0xf bank_mask:0xf bound_ctrl:1
	v_fmac_f32_dpp v4, v25, v224 row_newbcast:13 row_mask:0xf bank_mask:0xf bound_ctrl:1
	v_fmac_f32_dpp v3, v25, v224 row_newbcast:14 row_mask:0xf bank_mask:0xf bound_ctrl:1
	v_fmac_f32_dpp v2, v25, v224 row_newbcast:15 row_mask:0xf bank_mask:0xf bound_ctrl:1
	s_nop 0
	v_add_f32 v38, v38, v39
	s_nop 0
	s_nop 0
	v_mfma_f32_16x16x4_f32 v[232:235], v228, v38, 0
	ds_write_b64 v20, v[22:23] offset:22528
	v_fmac_f32_dpp v17, v26, v35 row_newbcast:0 row_mask:0xf bank_mask:0xf bound_ctrl:1
	v_fmac_f32_dpp v16, v26, v35 row_newbcast:1 row_mask:0xf bank_mask:0xf bound_ctrl:1
	v_fmac_f32_dpp v15, v26, v35 row_newbcast:2 row_mask:0xf bank_mask:0xf bound_ctrl:1
	v_fmac_f32_dpp v14, v26, v35 row_newbcast:3 row_mask:0xf bank_mask:0xf bound_ctrl:1
	v_fmac_f32_dpp v13, v26, v35 row_newbcast:4 row_mask:0xf bank_mask:0xf bound_ctrl:1
	v_fmac_f32_dpp v12, v26, v35 row_newbcast:5 row_mask:0xf bank_mask:0xf bound_ctrl:1
	v_fmac_f32_dpp v11, v26, v35 row_newbcast:6 row_mask:0xf bank_mask:0xf bound_ctrl:1
	v_fmac_f32_dpp v10, v26, v35 row_newbcast:7 row_mask:0xf bank_mask:0xf bound_ctrl:1
	v_fmac_f32_dpp v9, v26, v35 row_newbcast:8 row_mask:0xf bank_mask:0xf bound_ctrl:1
	v_fmac_f32_dpp v8, v26, v35 row_newbcast:9 row_mask:0xf bank_mask:0xf bound_ctrl:1
	v_fmac_f32_dpp v7, v26, v35 row_newbcast:10 row_mask:0xf bank_mask:0xf bound_ctrl:1
	v_fmac_f32_dpp v6, v26, v35 row_newbcast:11 row_mask:0xf bank_mask:0xf bound_ctrl:1
	v_fmac_f32_dpp v5, v26, v35 row_newbcast:12 row_mask:0xf bank_mask:0xf bound_ctrl:1
	v_fmac_f32_dpp v4, v26, v35 row_newbcast:13 row_mask:0xf bank_mask:0xf bound_ctrl:1
	v_fmac_f32_dpp v3, v26, v35 row_newbcast:14 row_mask:0xf bank_mask:0xf bound_ctrl:1
	v_fmac_f32_dpp v2, v26, v35 row_newbcast:15 row_mask:0xf bank_mask:0xf bound_ctrl:1
	v_mul_f32_dpp v22, v27, v17 row_newbcast:0 row_mask:0xf bank_mask:0xf bound_ctrl:1
	v_mul_f32_dpp v23, v27, v16 row_newbcast:1 row_mask:0xf bank_mask:0xf bound_ctrl:1
	v_fmac_f32_dpp v22, v27, v15 row_newbcast:2 row_mask:0xf bank_mask:0xf bound_ctrl:1
	v_fmac_f32_dpp v23, v27, v14 row_newbcast:3 row_mask:0xf bank_mask:0xf bound_ctrl:1
	v_fmac_f32_dpp v22, v27, v13 row_newbcast:4 row_mask:0xf bank_mask:0xf bound_ctrl:1
	v_fmac_f32_dpp v23, v27, v12 row_newbcast:5 row_mask:0xf bank_mask:0xf bound_ctrl:1
	v_fmac_f32_dpp v22, v27, v11 row_newbcast:6 row_mask:0xf bank_mask:0xf bound_ctrl:1
	v_fmac_f32_dpp v23, v27, v10 row_newbcast:7 row_mask:0xf bank_mask:0xf bound_ctrl:1
	s_nop 0
	v_fmac_f32_dpp v22, v27, v9 row_newbcast:8 row_mask:0xf bank_mask:0xf bound_ctrl:1
	v_fmac_f32_dpp v23, v27, v8 row_newbcast:9 row_mask:0xf bank_mask:0xf bound_ctrl:1
	v_fmac_f32_dpp v22, v27, v7 row_newbcast:10 row_mask:0xf bank_mask:0xf bound_ctrl:1
	v_fmac_f32_dpp v23, v27, v6 row_newbcast:11 row_mask:0xf bank_mask:0xf bound_ctrl:1
	s_nop 0
	v_fmac_f32_dpp v22, v27, v5 row_newbcast:12 row_mask:0xf bank_mask:0xf bound_ctrl:1
	v_fmac_f32_dpp v23, v27, v4 row_newbcast:13 row_mask:0xf bank_mask:0xf bound_ctrl:1
	v_fmac_f32_dpp v22, v27, v3 row_newbcast:14 row_mask:0xf bank_mask:0xf bound_ctrl:1
	v_fmac_f32_dpp v23, v27, v2 row_newbcast:15 row_mask:0xf bank_mask:0xf bound_ctrl:1
	s_waitcnt lgkmcnt(0)
	ds_read_b32 v34, v19 offset:24064
	ds_read2st64_b32 v[24:25], v21 offset0:30 offset1:46
	ds_read2st64_b32 v[26:27], v21 offset0:62 offset1:78
	v_mul_f32_dpp v39, v28, v17 row_newbcast:0 row_mask:0xf bank_mask:0xf bound_ctrl:1
	v_mul_f32_dpp v33, v28, v16 row_newbcast:1 row_mask:0xf bank_mask:0xf bound_ctrl:1
	v_fmac_f32_dpp v39, v28, v15 row_newbcast:2 row_mask:0xf bank_mask:0xf bound_ctrl:1
	v_fmac_f32_dpp v33, v28, v14 row_newbcast:3 row_mask:0xf bank_mask:0xf bound_ctrl:1
	v_fmac_f32_dpp v232, v229, v224 row_newbcast:12 row_mask:0xf bank_mask:0xf bound_ctrl:1
	v_fmac_f32_dpp v39, v28, v13 row_newbcast:4 row_mask:0xf bank_mask:0xf bound_ctrl:1
	v_fmac_f32_dpp v33, v28, v12 row_newbcast:5 row_mask:0xf bank_mask:0xf bound_ctrl:1
	v_fmac_f32_dpp v39, v28, v11 row_newbcast:6 row_mask:0xf bank_mask:0xf bound_ctrl:1
	v_fmac_f32_dpp v33, v28, v10 row_newbcast:7 row_mask:0xf bank_mask:0xf bound_ctrl:1
	v_fmac_f32_dpp v232, v230, v35 row_newbcast:12 row_mask:0xf bank_mask:0xf bound_ctrl:1
	v_fmac_f32_dpp v39, v28, v9 row_newbcast:8 row_mask:0xf bank_mask:0xf bound_ctrl:1
	v_fmac_f32_dpp v33, v28, v8 row_newbcast:9 row_mask:0xf bank_mask:0xf bound_ctrl:1
	v_fmac_f32_dpp v39, v28, v7 row_newbcast:10 row_mask:0xf bank_mask:0xf bound_ctrl:1
	v_fmac_f32_dpp v33, v28, v6 row_newbcast:11 row_mask:0xf bank_mask:0xf bound_ctrl:1
	s_nop 0
	v_fmac_f32_dpp v39, v28, v5 row_newbcast:12 row_mask:0xf bank_mask:0xf bound_ctrl:1
	v_fmac_f32_dpp v33, v28, v4 row_newbcast:13 row_mask:0xf bank_mask:0xf bound_ctrl:1
	v_fmac_f32_dpp v39, v28, v3 row_newbcast:14 row_mask:0xf bank_mask:0xf bound_ctrl:1
	v_fmac_f32_dpp v33, v28, v2 row_newbcast:15 row_mask:0xf bank_mask:0xf bound_ctrl:1
	v_fmac_f32_dpp v17, v29, v232 row_newbcast:0 row_mask:0xf bank_mask:0xf bound_ctrl:1
	v_fmac_f32_dpp v16, v29, v232 row_newbcast:1 row_mask:0xf bank_mask:0xf bound_ctrl:1
	v_fmac_f32_dpp v15, v29, v232 row_newbcast:2 row_mask:0xf bank_mask:0xf bound_ctrl:1
	v_fmac_f32_dpp v14, v29, v232 row_newbcast:3 row_mask:0xf bank_mask:0xf bound_ctrl:1
	v_fmac_f32_dpp v13, v29, v232 row_newbcast:4 row_mask:0xf bank_mask:0xf bound_ctrl:1
	v_fmac_f32_dpp v12, v29, v232 row_newbcast:5 row_mask:0xf bank_mask:0xf bound_ctrl:1
	v_fmac_f32_dpp v11, v29, v232 row_newbcast:6 row_mask:0xf bank_mask:0xf bound_ctrl:1
	v_fmac_f32_dpp v10, v29, v232 row_newbcast:7 row_mask:0xf bank_mask:0xf bound_ctrl:1
	v_fmac_f32_dpp v9, v29, v232 row_newbcast:8 row_mask:0xf bank_mask:0xf bound_ctrl:1
	v_fmac_f32_dpp v8, v29, v232 row_newbcast:9 row_mask:0xf bank_mask:0xf bound_ctrl:1
	v_fmac_f32_dpp v7, v29, v232 row_newbcast:10 row_mask:0xf bank_mask:0xf bound_ctrl:1
	v_fmac_f32_dpp v6, v29, v232 row_newbcast:11 row_mask:0xf bank_mask:0xf bound_ctrl:1
	v_fmac_f32_dpp v5, v29, v232 row_newbcast:12 row_mask:0xf bank_mask:0xf bound_ctrl:1
	v_fmac_f32_dpp v4, v29, v232 row_newbcast:13 row_mask:0xf bank_mask:0xf bound_ctrl:1
	v_fmac_f32_dpp v3, v29, v232 row_newbcast:14 row_mask:0xf bank_mask:0xf bound_ctrl:1
	v_fmac_f32_dpp v2, v29, v232 row_newbcast:15 row_mask:0xf bank_mask:0xf bound_ctrl:1
	s_nop 0
	v_add_f32 v39, v39, v33
	s_nop 0
	s_nop 0
	v_mfma_f32_16x16x4_f32 v[224:227], v228, v39, 0
	ds_write_b64 v20, v[22:23] offset:24576
	v_fmac_f32_dpp v17, v30, v37 row_newbcast:0 row_mask:0xf bank_mask:0xf bound_ctrl:1
	v_fmac_f32_dpp v16, v30, v37 row_newbcast:1 row_mask:0xf bank_mask:0xf bound_ctrl:1
	v_fmac_f32_dpp v15, v30, v37 row_newbcast:2 row_mask:0xf bank_mask:0xf bound_ctrl:1
	v_fmac_f32_dpp v14, v30, v37 row_newbcast:3 row_mask:0xf bank_mask:0xf bound_ctrl:1
	v_fmac_f32_dpp v13, v30, v37 row_newbcast:4 row_mask:0xf bank_mask:0xf bound_ctrl:1
	v_fmac_f32_dpp v12, v30, v37 row_newbcast:5 row_mask:0xf bank_mask:0xf bound_ctrl:1
	v_fmac_f32_dpp v11, v30, v37 row_newbcast:6 row_mask:0xf bank_mask:0xf bound_ctrl:1
	v_fmac_f32_dpp v10, v30, v37 row_newbcast:7 row_mask:0xf bank_mask:0xf bound_ctrl:1
	v_fmac_f32_dpp v9, v30, v37 row_newbcast:8 row_mask:0xf bank_mask:0xf bound_ctrl:1
	v_fmac_f32_dpp v8, v30, v37 row_newbcast:9 row_mask:0xf bank_mask:0xf bound_ctrl:1
	v_fmac_f32_dpp v7, v30, v37 row_newbcast:10 row_mask:0xf bank_mask:0xf bound_ctrl:1
	v_fmac_f32_dpp v6, v30, v37 row_newbcast:11 row_mask:0xf bank_mask:0xf bound_ctrl:1
	v_fmac_f32_dpp v5, v30, v37 row_newbcast:12 row_mask:0xf bank_mask:0xf bound_ctrl:1
	v_fmac_f32_dpp v4, v30, v37 row_newbcast:13 row_mask:0xf bank_mask:0xf bound_ctrl:1
	v_fmac_f32_dpp v3, v30, v37 row_newbcast:14 row_mask:0xf bank_mask:0xf bound_ctrl:1
	v_fmac_f32_dpp v2, v30, v37 row_newbcast:15 row_mask:0xf bank_mask:0xf bound_ctrl:1
	v_mul_f32_dpp v28, v31, v17 row_newbcast:0 row_mask:0xf bank_mask:0xf bound_ctrl:1
	v_mul_f32_dpp v29, v31, v16 row_newbcast:1 row_mask:0xf bank_mask:0xf bound_ctrl:1
	v_fmac_f32_dpp v28, v31, v15 row_newbcast:2 row_mask:0xf bank_mask:0xf bound_ctrl:1
	v_fmac_f32_dpp v29, v31, v14 row_newbcast:3 row_mask:0xf bank_mask:0xf bound_ctrl:1
	v_fmac_f32_dpp v28, v31, v13 row_newbcast:4 row_mask:0xf bank_mask:0xf bound_ctrl:1
	v_fmac_f32_dpp v29, v31, v12 row_newbcast:5 row_mask:0xf bank_mask:0xf bound_ctrl:1
	v_fmac_f32_dpp v28, v31, v11 row_newbcast:6 row_mask:0xf bank_mask:0xf bound_ctrl:1
	v_fmac_f32_dpp v29, v31, v10 row_newbcast:7 row_mask:0xf bank_mask:0xf bound_ctrl:1
	s_nop 0
	v_fmac_f32_dpp v28, v31, v9 row_newbcast:8 row_mask:0xf bank_mask:0xf bound_ctrl:1
	v_fmac_f32_dpp v29, v31, v8 row_newbcast:9 row_mask:0xf bank_mask:0xf bound_ctrl:1
	v_fmac_f32_dpp v28, v31, v7 row_newbcast:10 row_mask:0xf bank_mask:0xf bound_ctrl:1
	v_fmac_f32_dpp v29, v31, v6 row_newbcast:11 row_mask:0xf bank_mask:0xf bound_ctrl:1
	s_nop 0
	v_fmac_f32_dpp v28, v31, v5 row_newbcast:12 row_mask:0xf bank_mask:0xf bound_ctrl:1
	v_fmac_f32_dpp v29, v31, v4 row_newbcast:13 row_mask:0xf bank_mask:0xf bound_ctrl:1
	v_fmac_f32_dpp v28, v31, v3 row_newbcast:14 row_mask:0xf bank_mask:0xf bound_ctrl:1
	v_fmac_f32_dpp v29, v31, v2 row_newbcast:15 row_mask:0xf bank_mask:0xf bound_ctrl:1
	s_waitcnt lgkmcnt(0)
	ds_read_b32 v19, v19 offset:24320
	ds_read2st64_b32 v[30:31], v21 offset0:31 offset1:47
	ds_read2st64_b32 v[32:33], v21 offset0:63 offset1:79
	v_mul_f32_dpp v22, v24, v17 row_newbcast:0 row_mask:0xf bank_mask:0xf bound_ctrl:1
	v_mul_f32_dpp v35, v24, v16 row_newbcast:1 row_mask:0xf bank_mask:0xf bound_ctrl:1
	v_fmac_f32_dpp v22, v24, v15 row_newbcast:2 row_mask:0xf bank_mask:0xf bound_ctrl:1
	v_fmac_f32_dpp v35, v24, v14 row_newbcast:3 row_mask:0xf bank_mask:0xf bound_ctrl:1
	v_fmac_f32_dpp v224, v229, v232 row_newbcast:13 row_mask:0xf bank_mask:0xf bound_ctrl:1
	v_fmac_f32_dpp v22, v24, v13 row_newbcast:4 row_mask:0xf bank_mask:0xf bound_ctrl:1
	v_fmac_f32_dpp v35, v24, v12 row_newbcast:5 row_mask:0xf bank_mask:0xf bound_ctrl:1
	v_fmac_f32_dpp v22, v24, v11 row_newbcast:6 row_mask:0xf bank_mask:0xf bound_ctrl:1
	v_fmac_f32_dpp v35, v24, v10 row_newbcast:7 row_mask:0xf bank_mask:0xf bound_ctrl:1
	v_fmac_f32_dpp v224, v230, v37 row_newbcast:13 row_mask:0xf bank_mask:0xf bound_ctrl:1
	v_fmac_f32_dpp v22, v24, v9 row_newbcast:8 row_mask:0xf bank_mask:0xf bound_ctrl:1
	v_fmac_f32_dpp v35, v24, v8 row_newbcast:9 row_mask:0xf bank_mask:0xf bound_ctrl:1
	v_fmac_f32_dpp v22, v24, v7 row_newbcast:10 row_mask:0xf bank_mask:0xf bound_ctrl:1
	v_fmac_f32_dpp v35, v24, v6 row_newbcast:11 row_mask:0xf bank_mask:0xf bound_ctrl:1
	s_nop 0
	v_fmac_f32_dpp v22, v24, v5 row_newbcast:12 row_mask:0xf bank_mask:0xf bound_ctrl:1
	v_fmac_f32_dpp v35, v24, v4 row_newbcast:13 row_mask:0xf bank_mask:0xf bound_ctrl:1
	v_fmac_f32_dpp v22, v24, v3 row_newbcast:14 row_mask:0xf bank_mask:0xf bound_ctrl:1
	v_fmac_f32_dpp v35, v24, v2 row_newbcast:15 row_mask:0xf bank_mask:0xf bound_ctrl:1
	v_fmac_f32_dpp v17, v25, v224 row_newbcast:0 row_mask:0xf bank_mask:0xf bound_ctrl:1
	v_fmac_f32_dpp v16, v25, v224 row_newbcast:1 row_mask:0xf bank_mask:0xf bound_ctrl:1
	v_fmac_f32_dpp v15, v25, v224 row_newbcast:2 row_mask:0xf bank_mask:0xf bound_ctrl:1
	v_fmac_f32_dpp v14, v25, v224 row_newbcast:3 row_mask:0xf bank_mask:0xf bound_ctrl:1
	v_fmac_f32_dpp v13, v25, v224 row_newbcast:4 row_mask:0xf bank_mask:0xf bound_ctrl:1
	v_fmac_f32_dpp v12, v25, v224 row_newbcast:5 row_mask:0xf bank_mask:0xf bound_ctrl:1
	v_fmac_f32_dpp v11, v25, v224 row_newbcast:6 row_mask:0xf bank_mask:0xf bound_ctrl:1
	v_fmac_f32_dpp v10, v25, v224 row_newbcast:7 row_mask:0xf bank_mask:0xf bound_ctrl:1
	v_fmac_f32_dpp v9, v25, v224 row_newbcast:8 row_mask:0xf bank_mask:0xf bound_ctrl:1
	v_fmac_f32_dpp v8, v25, v224 row_newbcast:9 row_mask:0xf bank_mask:0xf bound_ctrl:1
	v_fmac_f32_dpp v7, v25, v224 row_newbcast:10 row_mask:0xf bank_mask:0xf bound_ctrl:1
	v_fmac_f32_dpp v6, v25, v224 row_newbcast:11 row_mask:0xf bank_mask:0xf bound_ctrl:1
	v_fmac_f32_dpp v5, v25, v224 row_newbcast:12 row_mask:0xf bank_mask:0xf bound_ctrl:1
	v_fmac_f32_dpp v4, v25, v224 row_newbcast:13 row_mask:0xf bank_mask:0xf bound_ctrl:1
	v_fmac_f32_dpp v3, v25, v224 row_newbcast:14 row_mask:0xf bank_mask:0xf bound_ctrl:1
	v_fmac_f32_dpp v2, v25, v224 row_newbcast:15 row_mask:0xf bank_mask:0xf bound_ctrl:1
	s_nop 0
	v_add_f32 v22, v22, v35
	s_nop 0
	s_nop 0
	v_mfma_f32_16x16x4_f32 v[232:235], v228, v22, 0
	ds_write_b64 v20, v[28:29] offset:26624
	v_fmac_f32_dpp v17, v26, v34 row_newbcast:0 row_mask:0xf bank_mask:0xf bound_ctrl:1
	v_fmac_f32_dpp v16, v26, v34 row_newbcast:1 row_mask:0xf bank_mask:0xf bound_ctrl:1
	v_fmac_f32_dpp v15, v26, v34 row_newbcast:2 row_mask:0xf bank_mask:0xf bound_ctrl:1
	v_fmac_f32_dpp v14, v26, v34 row_newbcast:3 row_mask:0xf bank_mask:0xf bound_ctrl:1
	v_fmac_f32_dpp v13, v26, v34 row_newbcast:4 row_mask:0xf bank_mask:0xf bound_ctrl:1
	v_fmac_f32_dpp v12, v26, v34 row_newbcast:5 row_mask:0xf bank_mask:0xf bound_ctrl:1
	v_fmac_f32_dpp v11, v26, v34 row_newbcast:6 row_mask:0xf bank_mask:0xf bound_ctrl:1
	v_fmac_f32_dpp v10, v26, v34 row_newbcast:7 row_mask:0xf bank_mask:0xf bound_ctrl:1
	v_fmac_f32_dpp v9, v26, v34 row_newbcast:8 row_mask:0xf bank_mask:0xf bound_ctrl:1
	v_fmac_f32_dpp v8, v26, v34 row_newbcast:9 row_mask:0xf bank_mask:0xf bound_ctrl:1
	v_fmac_f32_dpp v7, v26, v34 row_newbcast:10 row_mask:0xf bank_mask:0xf bound_ctrl:1
	v_fmac_f32_dpp v6, v26, v34 row_newbcast:11 row_mask:0xf bank_mask:0xf bound_ctrl:1
	v_fmac_f32_dpp v5, v26, v34 row_newbcast:12 row_mask:0xf bank_mask:0xf bound_ctrl:1
	v_fmac_f32_dpp v4, v26, v34 row_newbcast:13 row_mask:0xf bank_mask:0xf bound_ctrl:1
	v_fmac_f32_dpp v3, v26, v34 row_newbcast:14 row_mask:0xf bank_mask:0xf bound_ctrl:1
	v_fmac_f32_dpp v2, v26, v34 row_newbcast:15 row_mask:0xf bank_mask:0xf bound_ctrl:1
	v_mul_f32_dpp v24, v27, v17 row_newbcast:0 row_mask:0xf bank_mask:0xf bound_ctrl:1
	v_mul_f32_dpp v25, v27, v16 row_newbcast:1 row_mask:0xf bank_mask:0xf bound_ctrl:1
	v_fmac_f32_dpp v24, v27, v15 row_newbcast:2 row_mask:0xf bank_mask:0xf bound_ctrl:1
	v_fmac_f32_dpp v25, v27, v14 row_newbcast:3 row_mask:0xf bank_mask:0xf bound_ctrl:1
	v_fmac_f32_dpp v24, v27, v13 row_newbcast:4 row_mask:0xf bank_mask:0xf bound_ctrl:1
	v_fmac_f32_dpp v25, v27, v12 row_newbcast:5 row_mask:0xf bank_mask:0xf bound_ctrl:1
	v_fmac_f32_dpp v24, v27, v11 row_newbcast:6 row_mask:0xf bank_mask:0xf bound_ctrl:1
	v_fmac_f32_dpp v25, v27, v10 row_newbcast:7 row_mask:0xf bank_mask:0xf bound_ctrl:1
	s_nop 0
	v_fmac_f32_dpp v24, v27, v9 row_newbcast:8 row_mask:0xf bank_mask:0xf bound_ctrl:1
	v_fmac_f32_dpp v25, v27, v8 row_newbcast:9 row_mask:0xf bank_mask:0xf bound_ctrl:1
	v_fmac_f32_dpp v24, v27, v7 row_newbcast:10 row_mask:0xf bank_mask:0xf bound_ctrl:1
	v_fmac_f32_dpp v25, v27, v6 row_newbcast:11 row_mask:0xf bank_mask:0xf bound_ctrl:1
	s_nop 0
	v_fmac_f32_dpp v24, v27, v5 row_newbcast:12 row_mask:0xf bank_mask:0xf bound_ctrl:1
	v_fmac_f32_dpp v25, v27, v4 row_newbcast:13 row_mask:0xf bank_mask:0xf bound_ctrl:1
	v_fmac_f32_dpp v24, v27, v3 row_newbcast:14 row_mask:0xf bank_mask:0xf bound_ctrl:1
	v_fmac_f32_dpp v25, v27, v2 row_newbcast:15 row_mask:0xf bank_mask:0xf bound_ctrl:1
	s_waitcnt lgkmcnt(0)
	v_mul_f32_dpp v18, v30, v17 row_newbcast:0 row_mask:0xf bank_mask:0xf bound_ctrl:1
	v_mul_f32_dpp v27, v30, v16 row_newbcast:1 row_mask:0xf bank_mask:0xf bound_ctrl:1
	v_fmac_f32_dpp v18, v30, v15 row_newbcast:2 row_mask:0xf bank_mask:0xf bound_ctrl:1
	v_fmac_f32_dpp v27, v30, v14 row_newbcast:3 row_mask:0xf bank_mask:0xf bound_ctrl:1
	s_nop 0
	v_fmac_f32_dpp v18, v30, v13 row_newbcast:4 row_mask:0xf bank_mask:0xf bound_ctrl:1
	v_fmac_f32_dpp v27, v30, v12 row_newbcast:5 row_mask:0xf bank_mask:0xf bound_ctrl:1
	v_fmac_f32_dpp v18, v30, v11 row_newbcast:6 row_mask:0xf bank_mask:0xf bound_ctrl:1
	v_fmac_f32_dpp v27, v30, v10 row_newbcast:7 row_mask:0xf bank_mask:0xf bound_ctrl:1
	v_fmac_f32_dpp v232, v229, v224 row_newbcast:14 row_mask:0xf bank_mask:0xf bound_ctrl:1
	v_fmac_f32_dpp v18, v30, v9 row_newbcast:8 row_mask:0xf bank_mask:0xf bound_ctrl:1
	v_fmac_f32_dpp v27, v30, v8 row_newbcast:9 row_mask:0xf bank_mask:0xf bound_ctrl:1
	v_fmac_f32_dpp v18, v30, v7 row_newbcast:10 row_mask:0xf bank_mask:0xf bound_ctrl:1
	v_fmac_f32_dpp v27, v30, v6 row_newbcast:11 row_mask:0xf bank_mask:0xf bound_ctrl:1
	v_fmac_f32_dpp v232, v230, v34 row_newbcast:14 row_mask:0xf bank_mask:0xf bound_ctrl:1
	v_fmac_f32_dpp v18, v30, v5 row_newbcast:12 row_mask:0xf bank_mask:0xf bound_ctrl:1
	v_fmac_f32_dpp v27, v30, v4 row_newbcast:13 row_mask:0xf bank_mask:0xf bound_ctrl:1
	v_fmac_f32_dpp v18, v30, v3 row_newbcast:14 row_mask:0xf bank_mask:0xf bound_ctrl:1
	v_fmac_f32_dpp v27, v30, v2 row_newbcast:15 row_mask:0xf bank_mask:0xf bound_ctrl:1
	v_fmac_f32_dpp v17, v31, v232 row_newbcast:0 row_mask:0xf bank_mask:0xf bound_ctrl:1
	v_fmac_f32_dpp v16, v31, v232 row_newbcast:1 row_mask:0xf bank_mask:0xf bound_ctrl:1
	v_fmac_f32_dpp v15, v31, v232 row_newbcast:2 row_mask:0xf bank_mask:0xf bound_ctrl:1
	v_fmac_f32_dpp v14, v31, v232 row_newbcast:3 row_mask:0xf bank_mask:0xf bound_ctrl:1
	v_fmac_f32_dpp v13, v31, v232 row_newbcast:4 row_mask:0xf bank_mask:0xf bound_ctrl:1
	v_fmac_f32_dpp v12, v31, v232 row_newbcast:5 row_mask:0xf bank_mask:0xf bound_ctrl:1
	v_fmac_f32_dpp v11, v31, v232 row_newbcast:6 row_mask:0xf bank_mask:0xf bound_ctrl:1
	v_fmac_f32_dpp v10, v31, v232 row_newbcast:7 row_mask:0xf bank_mask:0xf bound_ctrl:1
	v_fmac_f32_dpp v9, v31, v232 row_newbcast:8 row_mask:0xf bank_mask:0xf bound_ctrl:1
	v_fmac_f32_dpp v8, v31, v232 row_newbcast:9 row_mask:0xf bank_mask:0xf bound_ctrl:1
	v_fmac_f32_dpp v7, v31, v232 row_newbcast:10 row_mask:0xf bank_mask:0xf bound_ctrl:1
	v_fmac_f32_dpp v6, v31, v232 row_newbcast:11 row_mask:0xf bank_mask:0xf bound_ctrl:1
	v_fmac_f32_dpp v5, v31, v232 row_newbcast:12 row_mask:0xf bank_mask:0xf bound_ctrl:1
	v_fmac_f32_dpp v4, v31, v232 row_newbcast:13 row_mask:0xf bank_mask:0xf bound_ctrl:1
	v_fmac_f32_dpp v3, v31, v232 row_newbcast:14 row_mask:0xf bank_mask:0xf bound_ctrl:1
	v_fmac_f32_dpp v2, v31, v232 row_newbcast:15 row_mask:0xf bank_mask:0xf bound_ctrl:1
	s_nop 0
	v_add_f32 v18, v18, v27
	s_nop 0
	s_nop 0
	v_mfma_f32_16x16x4_f32 v[224:227], v228, v18, 0
	ds_write_b64 v20, v[24:25] offset:28672
	ds_read_b32 v21, v21 offset:3840
	v_fmac_f32_dpp v17, v32, v19 row_newbcast:0 row_mask:0xf bank_mask:0xf bound_ctrl:1
	v_fmac_f32_dpp v16, v32, v19 row_newbcast:1 row_mask:0xf bank_mask:0xf bound_ctrl:1
	v_fmac_f32_dpp v15, v32, v19 row_newbcast:2 row_mask:0xf bank_mask:0xf bound_ctrl:1
	v_fmac_f32_dpp v14, v32, v19 row_newbcast:3 row_mask:0xf bank_mask:0xf bound_ctrl:1
	v_fmac_f32_dpp v13, v32, v19 row_newbcast:4 row_mask:0xf bank_mask:0xf bound_ctrl:1
	v_fmac_f32_dpp v12, v32, v19 row_newbcast:5 row_mask:0xf bank_mask:0xf bound_ctrl:1
	v_fmac_f32_dpp v11, v32, v19 row_newbcast:6 row_mask:0xf bank_mask:0xf bound_ctrl:1
	v_fmac_f32_dpp v10, v32, v19 row_newbcast:7 row_mask:0xf bank_mask:0xf bound_ctrl:1
	v_fmac_f32_dpp v9, v32, v19 row_newbcast:8 row_mask:0xf bank_mask:0xf bound_ctrl:1
	v_fmac_f32_dpp v8, v32, v19 row_newbcast:9 row_mask:0xf bank_mask:0xf bound_ctrl:1
	v_fmac_f32_dpp v7, v32, v19 row_newbcast:10 row_mask:0xf bank_mask:0xf bound_ctrl:1
	v_fmac_f32_dpp v6, v32, v19 row_newbcast:11 row_mask:0xf bank_mask:0xf bound_ctrl:1
	v_fmac_f32_dpp v5, v32, v19 row_newbcast:12 row_mask:0xf bank_mask:0xf bound_ctrl:1
	v_fmac_f32_dpp v4, v32, v19 row_newbcast:13 row_mask:0xf bank_mask:0xf bound_ctrl:1
	v_fmac_f32_dpp v3, v32, v19 row_newbcast:14 row_mask:0xf bank_mask:0xf bound_ctrl:1
	v_fmac_f32_dpp v2, v32, v19 row_newbcast:15 row_mask:0xf bank_mask:0xf bound_ctrl:1
	v_mul_f32_dpp v24, v33, v17 row_newbcast:0 row_mask:0xf bank_mask:0xf bound_ctrl:1
	v_mul_f32_dpp v25, v33, v16 row_newbcast:1 row_mask:0xf bank_mask:0xf bound_ctrl:1
	v_fmac_f32_dpp v24, v33, v15 row_newbcast:2 row_mask:0xf bank_mask:0xf bound_ctrl:1
	v_fmac_f32_dpp v25, v33, v14 row_newbcast:3 row_mask:0xf bank_mask:0xf bound_ctrl:1
	v_fmac_f32_dpp v24, v33, v13 row_newbcast:4 row_mask:0xf bank_mask:0xf bound_ctrl:1
	v_fmac_f32_dpp v25, v33, v12 row_newbcast:5 row_mask:0xf bank_mask:0xf bound_ctrl:1
	v_fmac_f32_dpp v24, v33, v11 row_newbcast:6 row_mask:0xf bank_mask:0xf bound_ctrl:1
	v_fmac_f32_dpp v25, v33, v10 row_newbcast:7 row_mask:0xf bank_mask:0xf bound_ctrl:1
	s_nop 0
	v_fmac_f32_dpp v24, v33, v9 row_newbcast:8 row_mask:0xf bank_mask:0xf bound_ctrl:1
	v_fmac_f32_dpp v25, v33, v8 row_newbcast:9 row_mask:0xf bank_mask:0xf bound_ctrl:1
	v_fmac_f32_dpp v24, v33, v7 row_newbcast:10 row_mask:0xf bank_mask:0xf bound_ctrl:1
	v_fmac_f32_dpp v25, v33, v6 row_newbcast:11 row_mask:0xf bank_mask:0xf bound_ctrl:1
	s_nop 0
	v_fmac_f32_dpp v24, v33, v5 row_newbcast:12 row_mask:0xf bank_mask:0xf bound_ctrl:1
	v_fmac_f32_dpp v25, v33, v4 row_newbcast:13 row_mask:0xf bank_mask:0xf bound_ctrl:1
	v_fmac_f32_dpp v24, v33, v3 row_newbcast:14 row_mask:0xf bank_mask:0xf bound_ctrl:1
	v_fmac_f32_dpp v25, v33, v2 row_newbcast:15 row_mask:0xf bank_mask:0xf bound_ctrl:1
	s_waitcnt lgkmcnt(0)
	v_mul_f32_dpp v17, v21, v17 row_newbcast:0 row_mask:0xf bank_mask:0xf bound_ctrl:1
	v_mul_f32_dpp v16, v21, v16 row_newbcast:1 row_mask:0xf bank_mask:0xf bound_ctrl:1
	v_mul_f32_dpp v15, v21, v15 row_newbcast:2 row_mask:0xf bank_mask:0xf bound_ctrl:1
	v_mul_f32_dpp v14, v21, v14 row_newbcast:3 row_mask:0xf bank_mask:0xf bound_ctrl:1
	v_mul_f32_dpp v13, v21, v13 row_newbcast:4 row_mask:0xf bank_mask:0xf bound_ctrl:1
	v_mul_f32_dpp v12, v21, v12 row_newbcast:5 row_mask:0xf bank_mask:0xf bound_ctrl:1
	v_mul_f32_dpp v11, v21, v11 row_newbcast:6 row_mask:0xf bank_mask:0xf bound_ctrl:1
	v_mul_f32_dpp v10, v21, v10 row_newbcast:7 row_mask:0xf bank_mask:0xf bound_ctrl:1
	v_mul_f32_dpp v9, v21, v9 row_newbcast:8 row_mask:0xf bank_mask:0xf bound_ctrl:1
	v_mul_f32_dpp v8, v21, v8 row_newbcast:9 row_mask:0xf bank_mask:0xf bound_ctrl:1
	v_mul_f32_dpp v7, v21, v7 row_newbcast:10 row_mask:0xf bank_mask:0xf bound_ctrl:1
	v_mul_f32_dpp v6, v21, v6 row_newbcast:11 row_mask:0xf bank_mask:0xf bound_ctrl:1
	v_mul_f32_dpp v5, v21, v5 row_newbcast:12 row_mask:0xf bank_mask:0xf bound_ctrl:1
	v_mul_f32_dpp v4, v21, v4 row_newbcast:13 row_mask:0xf bank_mask:0xf bound_ctrl:1
	v_mul_f32_dpp v3, v21, v3 row_newbcast:14 row_mask:0xf bank_mask:0xf bound_ctrl:1
	v_mul_f32_dpp v2, v21, v2 row_newbcast:15 row_mask:0xf bank_mask:0xf bound_ctrl:1
	ds_write_b64 v20, v[24:25] offset:30720
	s_waitcnt lgkmcnt(0)
	s_barrier
	s_cbranch_scc1 .LBB0_583
